# vmcnt and lgkmcnt waits before the K-loop barriers merged into one s_waitcnt
# speedup vs baseline: 1.0043x; 1.0043x over previous
.LBB0_236:
	s_add_i32 s12, s75, 2
	s_add_u32 s30, s28, 0xfff00080
	s_addc_u32 s31, s29, -1
	s_cmp_eq_u32 s72, s75
	s_cselect_b32 s35, s68, s31
	s_cselect_b32 s34, s69, s30
	s_cselect_b32 s31, s70, s74
	s_cselect_b32 s30, s71, s73
	s_cmpk_lt_i32 s3, 0x56
	s_cselect_b32 s36, s58, 0x2b00
	s_mov_b32 s37, 0xac00
	s_cselect_b32 s75, s37, 0x4000
	s_sub_i32 s36, s36, s33
	v_min3_i32 v5, s36, v174, 2
	v_sub_u32_e32 v174, v174, v5
	v_readfirstlane_b32 s78, v5
	s_max_i32 s36, s78, 0
	s_add_i32 s36, s33, s36
	s_add_i32 s76, s36, -1
	s_min_i32 s36, s33, s76
	s_mul_hi_i32 s37, s75, s36
	s_mul_i32 s36, s75, s36
	s_add_u32 s36, s38, s36
	s_addc_u32 s37, s39, s37
	s_mul_hi_i32 s77, s75, s76
	s_mul_i32 s75, s75, s76
	s_add_u32 s76, s38, s75
	global_load_dwordx4 v[152:155], v173, s[36:37] nt
	s_addc_u32 s77, s39, s77
	global_load_dwordx4 v[164:167], v173, s[76:77] nt
	s_add_i32 s33, s78, s33
	ds_read_b128 v[168:171], v160
	ds_read_b128 v[176:179], v160 offset:1024
	ds_read_b128 v[180:183], v160 offset:2048
	ds_read_b128 v[184:187], v160 offset:3072
	ds_read_b128 v[188:191], v160 offset:16384
	ds_read_b128 v[192:195], v160 offset:17408
	ds_read_b128 v[196:199], v160 offset:18432
	ds_read_b128 v[200:203], v160 offset:19456
	s_add_i32 m0, s49, 0xc000
	ds_read_b128 v[204:207], v163
	ds_read_b128 v[208:211], v163 offset:1024
	ds_read_b128 v[212:215], v163 offset:2048
	ds_read_b128 v[216:219], v163 offset:3072
	ds_read_b128 v[220:223], v163 offset:4096
	ds_read_b128 v[224:227], v163 offset:5120
	ds_read_b128 v[228:231], v163 offset:6144
	global_load_lds_dwordx4 v146, s[28:29]
	s_add_i32 m0, s49, 0xe000
	ds_read_b128 v[236:239], v163 offset:7168
	global_load_lds_dwordx4 v148, s[28:29]
	s_waitcnt vmcnt(10) lgkmcnt(0)
	s_barrier
	s_setprio 1
	v_mfma_f32_16x16x32_bf16 v[132:135], v[168:171], v[204:207], v[132:135]
	v_mfma_f32_16x16x32_bf16 v[128:131], v[180:183], v[204:207], v[128:131]
	v_mfma_f32_16x16x32_bf16 v[116:119], v[168:171], v[212:215], v[116:119]
	v_mfma_f32_16x16x32_bf16 v[112:115], v[180:183], v[212:215], v[112:115]
	v_mfma_f32_16x16x32_bf16 v[100:103], v[168:171], v[220:223], v[100:103]
	v_mfma_f32_16x16x32_bf16 v[96:99], v[180:183], v[220:223], v[96:99]
	v_mfma_f32_16x16x32_bf16 v[84:87], v[168:171], v[228:231], v[84:87]
	v_mfma_f32_16x16x32_bf16 v[80:83], v[180:183], v[228:231], v[80:83]
	v_mfma_f32_16x16x32_bf16 v[132:135], v[176:179], v[208:211], v[132:135]
	v_mfma_f32_16x16x32_bf16 v[128:131], v[184:187], v[208:211], v[128:131]
	v_mfma_f32_16x16x32_bf16 v[116:119], v[176:179], v[216:219], v[116:119]
	v_mfma_f32_16x16x32_bf16 v[112:115], v[184:187], v[216:219], v[112:115]
	v_mfma_f32_16x16x32_bf16 v[100:103], v[176:179], v[224:227], v[100:103]
	v_mfma_f32_16x16x32_bf16 v[96:99], v[184:187], v[224:227], v[96:99]
	v_mfma_f32_16x16x32_bf16 v[84:87], v[176:179], v[236:239], v[84:87]
	v_mfma_f32_16x16x32_bf16 v[80:83], v[184:187], v[236:239], v[80:83]
	s_setprio 0
	s_setprio 1
	v_mfma_f32_16x16x32_bf16 v[124:127], v[188:191], v[204:207], v[124:127]
	v_mfma_f32_16x16x32_bf16 v[120:123], v[196:199], v[204:207], v[120:123]
	v_mfma_f32_16x16x32_bf16 v[108:111], v[188:191], v[212:215], v[108:111]
	v_mfma_f32_16x16x32_bf16 v[104:107], v[196:199], v[212:215], v[104:107]
	v_mfma_f32_16x16x32_bf16 v[92:95], v[188:191], v[220:223], v[92:95]
	v_mfma_f32_16x16x32_bf16 v[88:91], v[196:199], v[220:223], v[88:91]
	v_mfma_f32_16x16x32_bf16 v[76:79], v[188:191], v[228:231], v[76:79]
	v_mfma_f32_16x16x32_bf16 v[72:75], v[196:199], v[228:231], v[72:75]
	v_mfma_f32_16x16x32_bf16 v[124:127], v[192:195], v[208:211], v[124:127]
	v_mfma_f32_16x16x32_bf16 v[120:123], v[200:203], v[208:211], v[120:123]
	v_mfma_f32_16x16x32_bf16 v[108:111], v[192:195], v[216:219], v[108:111]
	v_mfma_f32_16x16x32_bf16 v[104:107], v[200:203], v[216:219], v[104:107]
	v_mfma_f32_16x16x32_bf16 v[92:95], v[192:195], v[224:227], v[92:95]
	v_mfma_f32_16x16x32_bf16 v[88:91], v[200:203], v[224:227], v[88:91]
	v_mfma_f32_16x16x32_bf16 v[76:79], v[192:195], v[236:239], v[76:79]
	v_mfma_f32_16x16x32_bf16 v[72:75], v[200:203], v[236:239], v[72:75]
	s_setprio 0
	s_barrier
	s_add_i32 s36, s59, s48
	s_mov_b32 m0, s36
	ds_read_b128 v[204:207], v163 offset:16384
	ds_read_b128 v[208:211], v163 offset:17408
	ds_read_b128 v[212:215], v163 offset:18432
	ds_read_b128 v[216:219], v163 offset:19456
	global_load_lds_dwordx4 v138, s[30:31]
	s_add_i32 m0, s36, 0x2000
	s_add_u32 s36, s30, 0x100000
	s_addc_u32 s37, s31, 0
	s_add_i32 s75, s60, s48
	global_load_lds_dwordx4 v142, s[30:31]
	s_mov_b32 m0, s75
	ds_read_b128 v[236:239], v163 offset:23552
	global_load_lds_dwordx4 v138, s[36:37]
	s_add_i32 m0, s75, 0x2000
	ds_read_b128 v[228:231], v163 offset:22528
	global_load_lds_dwordx4 v142, s[36:37]
	s_mov_b32 m0, s49
	ds_read_b128 v[224:227], v163 offset:21504
	global_load_lds_dwordx4 v136, s[34:35]
	s_mov_b32 m0, s50
	ds_read_b128 v[220:223], v163 offset:20480
	global_load_lds_dwordx4 v140, s[34:35]
	s_waitcnt vmcnt(10) lgkmcnt(0)
	s_barrier
	s_setprio 1
	v_mfma_f32_16x16x32_bf16 v[68:71], v[168:171], v[204:207], v[68:71]
	v_mfma_f32_16x16x32_bf16 v[64:67], v[180:183], v[204:207], v[64:67]
	v_mfma_f32_16x16x32_bf16 v[52:55], v[168:171], v[212:215], v[52:55]
	v_mfma_f32_16x16x32_bf16 v[48:51], v[180:183], v[212:215], v[48:51]
	v_mfma_f32_16x16x32_bf16 v[36:39], v[168:171], v[220:223], v[36:39]
	v_mfma_f32_16x16x32_bf16 v[32:35], v[180:183], v[220:223], v[32:35]
	v_mfma_f32_16x16x32_bf16 v[20:23], v[168:171], v[228:231], v[20:23]
	v_mfma_f32_16x16x32_bf16 v[16:19], v[180:183], v[228:231], v[16:19]
	v_mfma_f32_16x16x32_bf16 v[68:71], v[176:179], v[208:211], v[68:71]
	v_mfma_f32_16x16x32_bf16 v[64:67], v[184:187], v[208:211], v[64:67]
	v_mfma_f32_16x16x32_bf16 v[52:55], v[176:179], v[216:219], v[52:55]
	v_mfma_f32_16x16x32_bf16 v[48:51], v[184:187], v[216:219], v[48:51]
	v_mfma_f32_16x16x32_bf16 v[36:39], v[176:179], v[224:227], v[36:39]
	v_mfma_f32_16x16x32_bf16 v[32:35], v[184:187], v[224:227], v[32:35]
	v_mfma_f32_16x16x32_bf16 v[20:23], v[176:179], v[236:239], v[20:23]
	v_mfma_f32_16x16x32_bf16 v[16:19], v[184:187], v[236:239], v[16:19]
	s_setprio 0
	s_setprio 1
	v_mfma_f32_16x16x32_bf16 v[60:63], v[188:191], v[204:207], v[60:63]
	v_mfma_f32_16x16x32_bf16 v[56:59], v[196:199], v[204:207], v[56:59]
	v_mfma_f32_16x16x32_bf16 v[44:47], v[188:191], v[212:215], v[44:47]
	v_mfma_f32_16x16x32_bf16 v[40:43], v[196:199], v[212:215], v[40:43]
	v_mfma_f32_16x16x32_bf16 v[28:31], v[188:191], v[220:223], v[28:31]
	v_mfma_f32_16x16x32_bf16 v[24:27], v[196:199], v[220:223], v[24:27]
	v_mfma_f32_16x16x32_bf16 v[12:15], v[188:191], v[228:231], v[12:15]
	v_mfma_f32_16x16x32_bf16 v[6:9], v[196:199], v[228:231], v[8:11]
	v_mfma_f32_16x16x32_bf16 v[60:63], v[192:195], v[208:211], v[60:63]
	v_mfma_f32_16x16x32_bf16 v[56:59], v[200:203], v[208:211], v[56:59]
	v_mfma_f32_16x16x32_bf16 v[44:47], v[192:195], v[216:219], v[44:47]
	v_mfma_f32_16x16x32_bf16 v[40:43], v[200:203], v[216:219], v[40:43]
	v_mfma_f32_16x16x32_bf16 v[28:31], v[192:195], v[224:227], v[28:31]
	v_mfma_f32_16x16x32_bf16 v[24:27], v[200:203], v[224:227], v[24:27]
	v_mfma_f32_16x16x32_bf16 v[12:15], v[192:195], v[236:239], v[12:15]
	v_mfma_f32_16x16x32_bf16 v[6:9], v[200:203], v[236:239], v[6:9]
	s_setprio 0
	s_barrier
	s_add_i32 s36, 0, 0x18000
	s_add_i32 s37, 0, 0x1c000
	ds_read_b128 v[168:171], v160 offset:32768
	ds_read_b128 v[176:179], v160 offset:33792
	ds_read_b128 v[180:183], v160 offset:34816
	ds_read_b128 v[184:187], v160 offset:35840
	ds_read_b128 v[188:191], v160 offset:49152
	ds_read_b128 v[192:195], v160 offset:50176
	ds_read_b128 v[196:199], v160 offset:51200
	ds_read_b128 v[200:203], v160 offset:52224
	s_add_u32 s34, s34, 0x100000
	s_addc_u32 s35, s35, 0
	s_mov_b32 m0, s51
	ds_read_b128 v[204:207], v163 offset:32768
	ds_read_b128 v[208:211], v163 offset:33792
	ds_read_b128 v[212:215], v163 offset:34816
	ds_read_b128 v[216:219], v163 offset:35840
	ds_read_b128 v[220:223], v163 offset:36864
	ds_read_b128 v[224:227], v163 offset:37888
	ds_read_b128 v[228:231], v163 offset:38912
	global_load_lds_dwordx4 v136, s[34:35]
	s_mov_b32 m0, s52
	ds_read_b128 v[236:239], v163 offset:39936
	global_load_lds_dwordx4 v140, s[34:35]
	s_waitcnt vmcnt(8) lgkmcnt(0)
	s_barrier
	s_setprio 1
	v_mfma_f32_16x16x32_bf16 v[132:135], v[168:171], v[204:207], v[132:135]
	v_mfma_f32_16x16x32_bf16 v[128:131], v[180:183], v[204:207], v[128:131]
	v_mfma_f32_16x16x32_bf16 v[116:119], v[168:171], v[212:215], v[116:119]
	v_mfma_f32_16x16x32_bf16 v[112:115], v[180:183], v[212:215], v[112:115]
	v_mfma_f32_16x16x32_bf16 v[100:103], v[168:171], v[220:223], v[100:103]
	v_max3_f32 v0, v0, |v152|, |v164|
	v_mfma_f32_16x16x32_bf16 v[96:99], v[180:183], v[220:223], v[96:99]
	v_max3_f32 v1, v1, |v153|, |v165|
	v_mfma_f32_16x16x32_bf16 v[84:87], v[168:171], v[228:231], v[84:87]
	v_max3_f32 v2, v2, |v154|, |v166|
	v_mfma_f32_16x16x32_bf16 v[80:83], v[180:183], v[228:231], v[80:83]
	v_max3_f32 v3, v3, |v155|, |v167|
	v_mfma_f32_16x16x32_bf16 v[132:135], v[176:179], v[208:211], v[132:135]
	v_mfma_f32_16x16x32_bf16 v[128:131], v[184:187], v[208:211], v[128:131]
	v_mfma_f32_16x16x32_bf16 v[116:119], v[176:179], v[216:219], v[116:119]
	v_mfma_f32_16x16x32_bf16 v[112:115], v[184:187], v[216:219], v[112:115]
	v_mfma_f32_16x16x32_bf16 v[100:103], v[176:179], v[224:227], v[100:103]
	v_mfma_f32_16x16x32_bf16 v[96:99], v[184:187], v[224:227], v[96:99]
	v_mfma_f32_16x16x32_bf16 v[84:87], v[176:179], v[236:239], v[84:87]
	v_mfma_f32_16x16x32_bf16 v[80:83], v[184:187], v[236:239], v[80:83]
	s_setprio 0
	s_setprio 1
	v_mfma_f32_16x16x32_bf16 v[124:127], v[188:191], v[204:207], v[124:127]
	v_mfma_f32_16x16x32_bf16 v[120:123], v[196:199], v[204:207], v[120:123]
	v_mfma_f32_16x16x32_bf16 v[108:111], v[188:191], v[212:215], v[108:111]
	v_mfma_f32_16x16x32_bf16 v[104:107], v[196:199], v[212:215], v[104:107]
	v_mfma_f32_16x16x32_bf16 v[92:95], v[188:191], v[220:223], v[92:95]
	v_mfma_f32_16x16x32_bf16 v[88:91], v[196:199], v[220:223], v[88:91]
	v_mfma_f32_16x16x32_bf16 v[76:79], v[188:191], v[228:231], v[76:79]
	v_mfma_f32_16x16x32_bf16 v[72:75], v[196:199], v[228:231], v[72:75]
	v_mfma_f32_16x16x32_bf16 v[124:127], v[192:195], v[208:211], v[124:127]
	v_mfma_f32_16x16x32_bf16 v[120:123], v[200:203], v[208:211], v[120:123]
	v_mfma_f32_16x16x32_bf16 v[108:111], v[192:195], v[216:219], v[108:111]
	v_mfma_f32_16x16x32_bf16 v[104:107], v[200:203], v[216:219], v[104:107]
	v_mfma_f32_16x16x32_bf16 v[92:95], v[192:195], v[224:227], v[92:95]
	v_mfma_f32_16x16x32_bf16 v[88:91], v[200:203], v[224:227], v[88:91]
	v_mfma_f32_16x16x32_bf16 v[76:79], v[192:195], v[236:239], v[76:79]
	v_mfma_f32_16x16x32_bf16 v[72:75], v[200:203], v[236:239], v[72:75]
	s_setprio 0
	s_barrier
	s_add_u32 s98, s30, s10
	s_addc_u32 s99, s31, s11
	s_add_u32 s100, s34, s10
	s_addc_u32 s101, s35, s11
	s_sub_u32 s100, s100, 0x100000
	s_subb_u32 s101, s101, 0
	s_add_i32 s34, s36, s48
	s_mov_b32 m0, s34
	ds_read_b128 v[152:155], v163 offset:49152
	ds_read_b128 v[164:167], v163 offset:50176
	ds_read_b128 v[204:207], v163 offset:51200
	ds_read_b128 v[208:211], v163 offset:52224
	global_load_lds_dwordx4 v138, s[98:99]
	s_add_i32 m0, s34, 0x2000
	s_add_u32 s30, s30, 0x100080
	s_addc_u32 s31, s31, 0
	s_add_i32 s34, s37, s48
	global_load_lds_dwordx4 v142, s[98:99]
	s_mov_b32 m0, s34
	ds_read_b128 v[224:227], v163 offset:56320
	global_load_lds_dwordx4 v138, s[30:31]
	s_add_i32 m0, s34, 0x2000
	ds_read_b128 v[220:223], v163 offset:55296
	global_load_lds_dwordx4 v142, s[30:31]
	s_mov_b32 m0, s56
	ds_read_b128 v[216:219], v163 offset:54272
	global_load_lds_dwordx4 v136, s[100:101]
	s_mov_b32 m0, s57
	ds_read_b128 v[212:215], v163 offset:53248
	global_load_lds_dwordx4 v140, s[100:101]
	s_waitcnt vmcnt(8) lgkmcnt(0)
	s_barrier
	s_setprio 1
	v_mfma_f32_16x16x32_bf16 v[68:71], v[168:171], v[152:155], v[68:71]
	v_mfma_f32_16x16x32_bf16 v[64:67], v[180:183], v[152:155], v[64:67]
	v_mfma_f32_16x16x32_bf16 v[52:55], v[168:171], v[204:207], v[52:55]
	v_mfma_f32_16x16x32_bf16 v[48:51], v[180:183], v[204:207], v[48:51]
	v_mfma_f32_16x16x32_bf16 v[36:39], v[168:171], v[212:215], v[36:39]
	v_mfma_f32_16x16x32_bf16 v[32:35], v[180:183], v[212:215], v[32:35]
	v_mfma_f32_16x16x32_bf16 v[20:23], v[168:171], v[220:223], v[20:23]
	v_mfma_f32_16x16x32_bf16 v[16:19], v[180:183], v[220:223], v[16:19]
	v_mfma_f32_16x16x32_bf16 v[68:71], v[176:179], v[164:167], v[68:71]
	v_mfma_f32_16x16x32_bf16 v[64:67], v[184:187], v[164:167], v[64:67]
	v_mfma_f32_16x16x32_bf16 v[52:55], v[176:179], v[208:211], v[52:55]
	v_mfma_f32_16x16x32_bf16 v[48:51], v[184:187], v[208:211], v[48:51]
	v_mfma_f32_16x16x32_bf16 v[36:39], v[176:179], v[216:219], v[36:39]
	v_mfma_f32_16x16x32_bf16 v[32:35], v[184:187], v[216:219], v[32:35]
	v_mfma_f32_16x16x32_bf16 v[20:23], v[176:179], v[224:227], v[20:23]
	v_mfma_f32_16x16x32_bf16 v[16:19], v[184:187], v[224:227], v[16:19]
	s_setprio 0
	s_setprio 1
	v_mfma_f32_16x16x32_bf16 v[60:63], v[188:191], v[152:155], v[60:63]
	v_mfma_f32_16x16x32_bf16 v[56:59], v[196:199], v[152:155], v[56:59]
	v_mfma_f32_16x16x32_bf16 v[44:47], v[188:191], v[204:207], v[44:47]
	v_mfma_f32_16x16x32_bf16 v[40:43], v[196:199], v[204:207], v[40:43]
	v_mfma_f32_16x16x32_bf16 v[28:31], v[188:191], v[212:215], v[28:31]
	v_mfma_f32_16x16x32_bf16 v[24:27], v[196:199], v[212:215], v[24:27]
	v_mfma_f32_16x16x32_bf16 v[10:13], v[188:191], v[220:223], v[12:15]
	v_mfma_f32_16x16x32_bf16 v[6:9], v[196:199], v[220:223], v[6:9]
	v_mfma_f32_16x16x32_bf16 v[60:63], v[192:195], v[164:167], v[60:63]
	v_mfma_f32_16x16x32_bf16 v[56:59], v[200:203], v[164:167], v[56:59]
	v_mfma_f32_16x16x32_bf16 v[44:47], v[192:195], v[208:211], v[44:47]
	v_mfma_f32_16x16x32_bf16 v[40:43], v[200:203], v[208:211], v[40:43]
	v_mfma_f32_16x16x32_bf16 v[28:31], v[192:195], v[216:219], v[28:31]
	v_mfma_f32_16x16x32_bf16 v[24:27], v[200:203], v[216:219], v[24:27]
	v_mfma_f32_16x16x32_bf16 v[12:15], v[192:195], v[224:227], v[10:13]
	v_mfma_f32_16x16x32_bf16 v[8:11], v[200:203], v[224:227], v[6:9]
	s_setprio 0
	s_barrier
	s_add_u32 s28, s28, 0x100
	s_addc_u32 s29, s29, 0
	s_add_u32 s73, s73, 0x100
	s_addc_u32 s74, s74, 0
	s_cmp_ge_i32 s12, s67
	s_cbranch_scc0 .LBB0_221
	s_and_b64 vcc, exec, s[14:15]
	s_cbranch_vccz .LBB0_239

.Lp1i_body:
	s_add_i32 s8, s74, 2
	s_add_u32 s34, s30, 0xfff80080
	s_addc_u32 s35, s31, -1
	s_cmp_eq_u32 s71, s74
	s_cselect_b32 s37, s67, s35
	s_cselect_b32 s36, s68, s34
	s_cselect_b32 s35, s69, s73
	s_cselect_b32 s34, s70, s72
	ds_read_b128 v[160:163], v177
	ds_read_b128 v[164:167], v177 offset:1024
	ds_read_b128 v[168:171], v177 offset:2048
	ds_read_b128 v[182:185], v177 offset:3072
	ds_read_b128 v[186:189], v177 offset:16384
	ds_read_b128 v[190:193], v177 offset:17408
	ds_read_b128 v[194:197], v177 offset:18432
	ds_read_b128 v[198:201], v177 offset:19456
	s_add_i32 m0, s46, 0xc000
	ds_read_b128 v[202:205], v180
	ds_read_b128 v[206:209], v180 offset:1024
	ds_read_b128 v[210:213], v180 offset:2048
	ds_read_b128 v[214:217], v180 offset:3072
	ds_read_b128 v[218:221], v180 offset:4096
	ds_read_b128 v[222:225], v180 offset:5120
	ds_read_b128 v[226:229], v180 offset:6144
	global_load_lds_dwordx4 v146, s[30:31]
	s_add_i32 m0, s46, 0xe000
	ds_read_b128 v[230:233], v180 offset:7168
	global_load_lds_dwordx4 v148, s[30:31]
	s_waitcnt vmcnt(8) lgkmcnt(0)
	s_barrier
	s_setprio 1
	v_mfma_i32_16x16x64_i8 v[132:135], v[160:163], v[202:205], v[132:135]
	v_mfma_i32_16x16x64_i8 v[128:131], v[168:171], v[202:205], v[128:131]
	v_mfma_i32_16x16x64_i8 v[124:127], v[160:163], v[210:213], v[124:127]
	v_mfma_i32_16x16x64_i8 v[120:123], v[168:171], v[210:213], v[120:123]
	v_mfma_i32_16x16x64_i8 v[112:115], v[160:163], v[218:221], v[112:115]
	v_mfma_i32_16x16x64_i8 v[104:107], v[168:171], v[218:221], v[104:107]
	v_mfma_i32_16x16x64_i8 v[96:99], v[160:163], v[226:229], v[96:99]
	v_mfma_i32_16x16x64_i8 v[88:91], v[168:171], v[226:229], v[88:91]
	v_mfma_i32_16x16x64_i8 v[132:135], v[164:167], v[206:209], v[132:135]
	v_mfma_i32_16x16x64_i8 v[128:131], v[182:185], v[206:209], v[128:131]
	v_mfma_i32_16x16x64_i8 v[124:127], v[164:167], v[214:217], v[124:127]
	v_mfma_i32_16x16x64_i8 v[120:123], v[182:185], v[214:217], v[120:123]
	v_mfma_i32_16x16x64_i8 v[112:115], v[164:167], v[222:225], v[112:115]
	v_mfma_i32_16x16x64_i8 v[104:107], v[182:185], v[222:225], v[104:107]
	v_mfma_i32_16x16x64_i8 v[96:99], v[164:167], v[230:233], v[96:99]
	v_mfma_i32_16x16x64_i8 v[88:91], v[182:185], v[230:233], v[88:91]
	s_setprio 0
	s_setprio 1
	v_mfma_i32_16x16x64_i8 v[116:119], v[186:189], v[202:205], v[116:119]
	v_mfma_i32_16x16x64_i8 v[108:111], v[194:197], v[202:205], v[108:111]
	v_mfma_i32_16x16x64_i8 v[100:103], v[186:189], v[210:213], v[100:103]
	v_mfma_i32_16x16x64_i8 v[92:95], v[194:197], v[210:213], v[92:95]
	v_mfma_i32_16x16x64_i8 v[84:87], v[186:189], v[218:221], v[84:87]
	v_mfma_i32_16x16x64_i8 v[80:83], v[194:197], v[218:221], v[80:83]
	v_mfma_i32_16x16x64_i8 v[76:79], v[186:189], v[226:229], v[76:79]
	v_mfma_i32_16x16x64_i8 v[72:75], v[194:197], v[226:229], v[72:75]
	v_mfma_i32_16x16x64_i8 v[116:119], v[190:193], v[206:209], v[116:119]
	v_mfma_i32_16x16x64_i8 v[108:111], v[198:201], v[206:209], v[108:111]
	v_mfma_i32_16x16x64_i8 v[100:103], v[190:193], v[214:217], v[100:103]
	v_mfma_i32_16x16x64_i8 v[92:95], v[198:201], v[214:217], v[92:95]
	v_mfma_i32_16x16x64_i8 v[84:87], v[190:193], v[222:225], v[84:87]
	v_mfma_i32_16x16x64_i8 v[80:83], v[198:201], v[222:225], v[80:83]
	v_mfma_i32_16x16x64_i8 v[76:79], v[190:193], v[230:233], v[76:79]
	v_mfma_i32_16x16x64_i8 v[72:75], v[198:201], v[230:233], v[72:75]
	s_setprio 0
	s_barrier
	s_add_i32 s74, s57, s45
	s_mov_b32 m0, s74
	ds_read_b128 v[202:205], v180 offset:16384
	ds_read_b128 v[206:209], v180 offset:17408
	ds_read_b128 v[210:213], v180 offset:18432
	ds_read_b128 v[214:217], v180 offset:19456
	global_load_lds_dwordx4 v138, s[34:35]
	s_add_i32 m0, s74, 0x2000
	s_add_u32 s74, s34, 0x80000
	s_addc_u32 s75, s35, 0
	s_add_i32 s76, s58, s45
	global_load_lds_dwordx4 v142, s[34:35]
	s_mov_b32 m0, s76
	ds_read_b128 v[230:233], v180 offset:23552
	global_load_lds_dwordx4 v138, s[74:75]
	s_add_i32 m0, s76, 0x2000
	ds_read_b128 v[226:229], v180 offset:22528
	global_load_lds_dwordx4 v142, s[74:75]
	s_mov_b32 m0, s46
	ds_read_b128 v[222:225], v180 offset:21504
	global_load_lds_dwordx4 v136, s[36:37]
	s_mov_b32 m0, s47
	ds_read_b128 v[218:221], v180 offset:20480
	global_load_lds_dwordx4 v140, s[36:37]
	s_waitcnt vmcnt(8) lgkmcnt(0)
	s_barrier
	s_setprio 1
	v_mfma_i32_16x16x64_i8 v[68:71], v[160:163], v[202:205], v[68:71]
	v_mfma_i32_16x16x64_i8 v[64:67], v[168:171], v[202:205], v[64:67]
	v_mfma_i32_16x16x64_i8 v[60:63], v[160:163], v[210:213], v[60:63]
	v_mfma_i32_16x16x64_i8 v[56:59], v[168:171], v[210:213], v[56:59]
	v_mfma_i32_16x16x64_i8 v[48:51], v[160:163], v[218:221], v[48:51]
	v_mfma_i32_16x16x64_i8 v[40:43], v[168:171], v[218:221], v[40:43]
	v_mfma_i32_16x16x64_i8 v[32:35], v[160:163], v[226:229], v[32:35]
	v_mfma_i32_16x16x64_i8 v[24:27], v[168:171], v[226:229], v[24:27]
	v_mfma_i32_16x16x64_i8 v[68:71], v[164:167], v[206:209], v[68:71]
	v_mfma_i32_16x16x64_i8 v[64:67], v[182:185], v[206:209], v[64:67]
	v_mfma_i32_16x16x64_i8 v[60:63], v[164:167], v[214:217], v[60:63]
	v_mfma_i32_16x16x64_i8 v[56:59], v[182:185], v[214:217], v[56:59]
	v_mfma_i32_16x16x64_i8 v[48:51], v[164:167], v[222:225], v[48:51]
	v_mfma_i32_16x16x64_i8 v[40:43], v[182:185], v[222:225], v[40:43]
	v_mfma_i32_16x16x64_i8 v[32:35], v[164:167], v[230:233], v[32:35]
	v_mfma_i32_16x16x64_i8 v[24:27], v[182:185], v[230:233], v[24:27]
	s_setprio 0
	s_setprio 1
	v_mfma_i32_16x16x64_i8 v[52:55], v[186:189], v[202:205], v[52:55]
	v_mfma_i32_16x16x64_i8 v[44:47], v[194:197], v[202:205], v[44:47]
	v_mfma_i32_16x16x64_i8 v[36:39], v[186:189], v[210:213], v[36:39]
	v_mfma_i32_16x16x64_i8 v[28:31], v[194:197], v[210:213], v[28:31]
	v_mfma_i32_16x16x64_i8 v[20:23], v[186:189], v[218:221], v[20:23]
	v_mfma_i32_16x16x64_i8 v[16:19], v[194:197], v[218:221], v[16:19]
	v_mfma_i32_16x16x64_i8 v[12:15], v[186:189], v[226:229], v[12:15]
	v_mfma_i32_16x16x64_i8 v[6:9], v[194:197], v[226:229], v[8:11]
	v_mfma_i32_16x16x64_i8 v[52:55], v[190:193], v[206:209], v[52:55]
	v_mfma_i32_16x16x64_i8 v[44:47], v[198:201], v[206:209], v[44:47]
	v_mfma_i32_16x16x64_i8 v[36:39], v[190:193], v[214:217], v[36:39]
	v_mfma_i32_16x16x64_i8 v[28:31], v[198:201], v[214:217], v[28:31]
	v_mfma_i32_16x16x64_i8 v[20:23], v[190:193], v[222:225], v[20:23]
	v_mfma_i32_16x16x64_i8 v[16:19], v[198:201], v[222:225], v[16:19]
	v_mfma_i32_16x16x64_i8 v[12:15], v[190:193], v[230:233], v[12:15]
	v_mfma_i32_16x16x64_i8 v[6:9], v[198:201], v[230:233], v[6:9]
	s_setprio 0
	s_barrier
	s_add_i32 s74, 0, 0x18000
	s_add_i32 s75, 0, 0x1c000
	ds_read_b128 v[160:163], v177 offset:32768
	ds_read_b128 v[164:167], v177 offset:33792
	ds_read_b128 v[168:171], v177 offset:34816
	ds_read_b128 v[182:185], v177 offset:35840
	ds_read_b128 v[186:189], v177 offset:49152
	ds_read_b128 v[190:193], v177 offset:50176
	ds_read_b128 v[194:197], v177 offset:51200
	ds_read_b128 v[198:201], v177 offset:52224
	s_add_u32 s36, s36, 0x80000
	s_addc_u32 s37, s37, 0
	s_mov_b32 m0, s48
	ds_read_b128 v[202:205], v180 offset:32768
	ds_read_b128 v[206:209], v180 offset:33792
	ds_read_b128 v[210:213], v180 offset:34816
	ds_read_b128 v[214:217], v180 offset:35840
	ds_read_b128 v[218:221], v180 offset:36864
	ds_read_b128 v[222:225], v180 offset:37888
	ds_read_b128 v[226:229], v180 offset:38912
	global_load_lds_dwordx4 v136, s[36:37]
	s_mov_b32 m0, s49
	ds_read_b128 v[230:233], v180 offset:39936
	global_load_lds_dwordx4 v140, s[36:37]
	s_waitcnt vmcnt(8) lgkmcnt(0)
	s_barrier
	s_setprio 1
	v_mfma_i32_16x16x64_i8 v[132:135], v[160:163], v[202:205], v[132:135]
	v_mfma_i32_16x16x64_i8 v[128:131], v[168:171], v[202:205], v[128:131]
	v_mfma_i32_16x16x64_i8 v[124:127], v[160:163], v[210:213], v[124:127]
	v_mfma_i32_16x16x64_i8 v[120:123], v[168:171], v[210:213], v[120:123]
	v_mfma_i32_16x16x64_i8 v[112:115], v[160:163], v[218:221], v[112:115]
	v_mfma_i32_16x16x64_i8 v[104:107], v[168:171], v[218:221], v[104:107]
	v_mfma_i32_16x16x64_i8 v[96:99], v[160:163], v[226:229], v[96:99]
	v_mfma_i32_16x16x64_i8 v[88:91], v[168:171], v[226:229], v[88:91]
	v_mfma_i32_16x16x64_i8 v[132:135], v[164:167], v[206:209], v[132:135]
	v_mfma_i32_16x16x64_i8 v[128:131], v[182:185], v[206:209], v[128:131]
	v_mfma_i32_16x16x64_i8 v[124:127], v[164:167], v[214:217], v[124:127]
	v_mfma_i32_16x16x64_i8 v[120:123], v[182:185], v[214:217], v[120:123]
	v_mfma_i32_16x16x64_i8 v[112:115], v[164:167], v[222:225], v[112:115]
	v_mfma_i32_16x16x64_i8 v[104:107], v[182:185], v[222:225], v[104:107]
	v_mfma_i32_16x16x64_i8 v[96:99], v[164:167], v[230:233], v[96:99]
	v_mfma_i32_16x16x64_i8 v[88:91], v[182:185], v[230:233], v[88:91]
	s_setprio 0
	s_setprio 1
	v_mfma_i32_16x16x64_i8 v[116:119], v[186:189], v[202:205], v[116:119]
	v_mfma_i32_16x16x64_i8 v[108:111], v[194:197], v[202:205], v[108:111]
	v_mfma_i32_16x16x64_i8 v[100:103], v[186:189], v[210:213], v[100:103]
	v_mfma_i32_16x16x64_i8 v[92:95], v[194:197], v[210:213], v[92:95]
	v_mfma_i32_16x16x64_i8 v[84:87], v[186:189], v[218:221], v[84:87]
	v_mfma_i32_16x16x64_i8 v[80:83], v[194:197], v[218:221], v[80:83]
	v_mfma_i32_16x16x64_i8 v[76:79], v[186:189], v[226:229], v[76:79]
	v_mfma_i32_16x16x64_i8 v[72:75], v[194:197], v[226:229], v[72:75]
	v_mfma_i32_16x16x64_i8 v[116:119], v[190:193], v[206:209], v[116:119]
	v_mfma_i32_16x16x64_i8 v[108:111], v[198:201], v[206:209], v[108:111]
	v_mfma_i32_16x16x64_i8 v[100:103], v[190:193], v[214:217], v[100:103]
	v_mfma_i32_16x16x64_i8 v[92:95], v[198:201], v[214:217], v[92:95]
	v_mfma_i32_16x16x64_i8 v[84:87], v[190:193], v[222:225], v[84:87]
	v_mfma_i32_16x16x64_i8 v[80:83], v[198:201], v[222:225], v[80:83]
	v_mfma_i32_16x16x64_i8 v[76:79], v[190:193], v[230:233], v[76:79]
	v_mfma_i32_16x16x64_i8 v[72:75], v[198:201], v[230:233], v[72:75]
	s_setprio 0
	s_barrier
	s_add_u32 s98, s34, s14
	s_addc_u32 s99, s35, s15
	s_add_u32 s100, s36, s14
	s_addc_u32 s101, s37, s15
	s_sub_u32 s100, s100, 0x80000
	s_subb_u32 s101, s101, 0
	s_add_i32 s36, s74, s45
	s_mov_b32 m0, s36
	ds_read_b128 v[152:155], v180 offset:49152
	ds_read_b128 v[156:159], v180 offset:50176
	ds_read_b128 v[202:205], v180 offset:51200
	ds_read_b128 v[206:209], v180 offset:52224
	global_load_lds_dwordx4 v138, s[98:99]
	s_add_i32 m0, s36, 0x2000
	s_add_u32 s34, s34, 0x80080
	s_addc_u32 s35, s35, 0
	s_add_i32 s36, s75, s45
	global_load_lds_dwordx4 v142, s[98:99]
	s_mov_b32 m0, s36
	ds_read_b128 v[222:225], v180 offset:56320
	global_load_lds_dwordx4 v138, s[34:35]
	s_add_i32 m0, s36, 0x2000
	ds_read_b128 v[218:221], v180 offset:55296
	global_load_lds_dwordx4 v142, s[34:35]
	s_mov_b32 m0, s54
	ds_read_b128 v[214:217], v180 offset:54272
	global_load_lds_dwordx4 v136, s[100:101]
	s_mov_b32 m0, s55
	ds_read_b128 v[210:213], v180 offset:53248
	global_load_lds_dwordx4 v140, s[100:101]
	s_waitcnt vmcnt(8) lgkmcnt(0)
	s_barrier
	s_setprio 1
	v_mfma_i32_16x16x64_i8 v[68:71], v[160:163], v[152:155], v[68:71]
	v_mfma_i32_16x16x64_i8 v[64:67], v[168:171], v[152:155], v[64:67]
	v_mfma_i32_16x16x64_i8 v[60:63], v[160:163], v[202:205], v[60:63]
	v_mfma_i32_16x16x64_i8 v[56:59], v[168:171], v[202:205], v[56:59]
	v_mfma_i32_16x16x64_i8 v[48:51], v[160:163], v[210:213], v[48:51]
	v_mfma_i32_16x16x64_i8 v[40:43], v[168:171], v[210:213], v[40:43]
	v_mfma_i32_16x16x64_i8 v[32:35], v[160:163], v[218:221], v[32:35]
	v_mfma_i32_16x16x64_i8 v[24:27], v[168:171], v[218:221], v[24:27]
	v_mfma_i32_16x16x64_i8 v[68:71], v[164:167], v[156:159], v[68:71]
	v_mfma_i32_16x16x64_i8 v[64:67], v[182:185], v[156:159], v[64:67]
	v_mfma_i32_16x16x64_i8 v[60:63], v[164:167], v[206:209], v[60:63]
	v_mfma_i32_16x16x64_i8 v[56:59], v[182:185], v[206:209], v[56:59]
	v_mfma_i32_16x16x64_i8 v[48:51], v[164:167], v[214:217], v[48:51]
	v_mfma_i32_16x16x64_i8 v[40:43], v[182:185], v[214:217], v[40:43]
	v_mfma_i32_16x16x64_i8 v[32:35], v[164:167], v[222:225], v[32:35]
	v_mfma_i32_16x16x64_i8 v[24:27], v[182:185], v[222:225], v[24:27]
	s_setprio 0
	s_setprio 1
	v_mfma_i32_16x16x64_i8 v[52:55], v[186:189], v[152:155], v[52:55]
	v_mfma_i32_16x16x64_i8 v[44:47], v[194:197], v[152:155], v[44:47]
	v_mfma_i32_16x16x64_i8 v[36:39], v[186:189], v[202:205], v[36:39]
	v_mfma_i32_16x16x64_i8 v[28:31], v[194:197], v[202:205], v[28:31]
	v_mfma_i32_16x16x64_i8 v[20:23], v[186:189], v[210:213], v[20:23]
	v_mfma_i32_16x16x64_i8 v[16:19], v[194:197], v[210:213], v[16:19]
	v_mfma_i32_16x16x64_i8 v[10:13], v[186:189], v[218:221], v[12:15]
	v_mfma_i32_16x16x64_i8 v[6:9], v[194:197], v[218:221], v[6:9]
	v_mfma_i32_16x16x64_i8 v[52:55], v[190:193], v[156:159], v[52:55]
	v_mfma_i32_16x16x64_i8 v[44:47], v[198:201], v[156:159], v[44:47]
	v_mfma_i32_16x16x64_i8 v[36:39], v[190:193], v[206:209], v[36:39]
	v_mfma_i32_16x16x64_i8 v[28:31], v[198:201], v[206:209], v[28:31]
	v_mfma_i32_16x16x64_i8 v[20:23], v[190:193], v[214:217], v[20:23]
	v_mfma_i32_16x16x64_i8 v[16:19], v[198:201], v[214:217], v[16:19]
	v_mfma_i32_16x16x64_i8 v[12:15], v[190:193], v[222:225], v[10:13]
	v_mfma_i32_16x16x64_i8 v[8:11], v[198:201], v[222:225], v[6:9]
	s_setprio 0
	s_barrier
	s_add_u32 s30, s30, 0x100
	s_addc_u32 s31, s31, 0
	s_add_u32 s72, s72, 0x100
	s_addc_u32 s73, s73, 0
	s_cmp_ge_i32 s8, s66
	s_cbranch_scc0 .Lp1i_top
	s_branch .Lp1i_epi

.LBB0_327:
	s_add_i32 s8, s74, 2
	s_add_u32 s34, s30, 0xfff80080
	s_addc_u32 s35, s31, -1
	s_cmp_eq_u32 s71, s74
	s_cselect_b32 s37, s67, s35
	s_cselect_b32 s36, s68, s34
	s_cselect_b32 s35, s69, s73
	s_cselect_b32 s34, s70, s72
	s_cmpk_lt_i32 s3, 0x56
	s_cselect_b32 s74, s56, 0x2b00
	s_mov_b32 s75, 0xac00
	s_cselect_b32 s76, s75, 0x4000
	s_sub_i32 s74, s74, s33
	v_min3_i32 v5, s74, v174, 2
	v_sub_u32_e32 v174, v174, v5
	v_readfirstlane_b32 s78, v5
	s_max_i32 s74, s78, 0
	s_add_i32 s74, s33, s74
	s_add_i32 s77, s74, -1
	s_min_i32 s74, s33, s77
	s_mul_hi_i32 s75, s76, s74
	s_mul_i32 s74, s76, s74
	s_add_u32 s74, s38, s74
	s_addc_u32 s75, s39, s75
	s_mul_hi_i32 s79, s76, s77
	s_mul_i32 s76, s76, s77
	s_add_u32 s76, s38, s76
	global_load_dwordx4 v[152:155], v173, s[74:75] nt
	s_addc_u32 s77, s39, s79
	global_load_dwordx4 v[156:159], v173, s[76:77] nt
	s_add_i32 s33, s78, s33
	ds_read_b128 v[160:163], v177
	ds_read_b128 v[164:167], v177 offset:1024
	ds_read_b128 v[168:171], v177 offset:2048
	ds_read_b128 v[182:185], v177 offset:3072
	ds_read_b128 v[186:189], v177 offset:16384
	ds_read_b128 v[190:193], v177 offset:17408
	ds_read_b128 v[194:197], v177 offset:18432
	ds_read_b128 v[198:201], v177 offset:19456
	s_add_i32 m0, s46, 0xc000
	ds_read_b128 v[202:205], v180
	ds_read_b128 v[206:209], v180 offset:1024
	ds_read_b128 v[210:213], v180 offset:2048
	ds_read_b128 v[214:217], v180 offset:3072
	ds_read_b128 v[218:221], v180 offset:4096
	ds_read_b128 v[222:225], v180 offset:5120
	ds_read_b128 v[226:229], v180 offset:6144
	global_load_lds_dwordx4 v146, s[30:31]
	s_add_i32 m0, s46, 0xe000
	ds_read_b128 v[230:233], v180 offset:7168
	global_load_lds_dwordx4 v148, s[30:31]
	s_waitcnt vmcnt(10) lgkmcnt(0)
	s_barrier
	s_setprio 1
	v_mfma_i32_16x16x64_i8 v[132:135], v[160:163], v[202:205], v[132:135]
	v_mfma_i32_16x16x64_i8 v[128:131], v[168:171], v[202:205], v[128:131]
	v_mfma_i32_16x16x64_i8 v[124:127], v[160:163], v[210:213], v[124:127]
	v_mfma_i32_16x16x64_i8 v[120:123], v[168:171], v[210:213], v[120:123]
	v_mfma_i32_16x16x64_i8 v[112:115], v[160:163], v[218:221], v[112:115]
	v_mfma_i32_16x16x64_i8 v[104:107], v[168:171], v[218:221], v[104:107]
	v_mfma_i32_16x16x64_i8 v[96:99], v[160:163], v[226:229], v[96:99]
	v_mfma_i32_16x16x64_i8 v[88:91], v[168:171], v[226:229], v[88:91]
	v_mfma_i32_16x16x64_i8 v[132:135], v[164:167], v[206:209], v[132:135]
	v_mfma_i32_16x16x64_i8 v[128:131], v[182:185], v[206:209], v[128:131]
	v_mfma_i32_16x16x64_i8 v[124:127], v[164:167], v[214:217], v[124:127]
	v_mfma_i32_16x16x64_i8 v[120:123], v[182:185], v[214:217], v[120:123]
	v_mfma_i32_16x16x64_i8 v[112:115], v[164:167], v[222:225], v[112:115]
	v_mfma_i32_16x16x64_i8 v[104:107], v[182:185], v[222:225], v[104:107]
	v_mfma_i32_16x16x64_i8 v[96:99], v[164:167], v[230:233], v[96:99]
	v_mfma_i32_16x16x64_i8 v[88:91], v[182:185], v[230:233], v[88:91]
	s_setprio 0
	s_setprio 1
	v_mfma_i32_16x16x64_i8 v[116:119], v[186:189], v[202:205], v[116:119]
	v_mfma_i32_16x16x64_i8 v[108:111], v[194:197], v[202:205], v[108:111]
	v_mfma_i32_16x16x64_i8 v[100:103], v[186:189], v[210:213], v[100:103]
	v_mfma_i32_16x16x64_i8 v[92:95], v[194:197], v[210:213], v[92:95]
	v_mfma_i32_16x16x64_i8 v[84:87], v[186:189], v[218:221], v[84:87]
	v_mfma_i32_16x16x64_i8 v[80:83], v[194:197], v[218:221], v[80:83]
	v_mfma_i32_16x16x64_i8 v[76:79], v[186:189], v[226:229], v[76:79]
	v_mfma_i32_16x16x64_i8 v[72:75], v[194:197], v[226:229], v[72:75]
	v_mfma_i32_16x16x64_i8 v[116:119], v[190:193], v[206:209], v[116:119]
	v_mfma_i32_16x16x64_i8 v[108:111], v[198:201], v[206:209], v[108:111]
	v_mfma_i32_16x16x64_i8 v[100:103], v[190:193], v[214:217], v[100:103]
	v_mfma_i32_16x16x64_i8 v[92:95], v[198:201], v[214:217], v[92:95]
	v_mfma_i32_16x16x64_i8 v[84:87], v[190:193], v[222:225], v[84:87]
	v_mfma_i32_16x16x64_i8 v[80:83], v[198:201], v[222:225], v[80:83]
	v_mfma_i32_16x16x64_i8 v[76:79], v[190:193], v[230:233], v[76:79]
	v_mfma_i32_16x16x64_i8 v[72:75], v[198:201], v[230:233], v[72:75]
	s_setprio 0
	s_barrier
	s_add_i32 s74, s57, s45
	s_mov_b32 m0, s74
	ds_read_b128 v[202:205], v180 offset:16384
	ds_read_b128 v[206:209], v180 offset:17408
	ds_read_b128 v[210:213], v180 offset:18432
	ds_read_b128 v[214:217], v180 offset:19456
	global_load_lds_dwordx4 v138, s[34:35]
	s_add_i32 m0, s74, 0x2000
	s_add_u32 s74, s34, 0x80000
	s_addc_u32 s75, s35, 0
	s_add_i32 s76, s58, s45
	global_load_lds_dwordx4 v142, s[34:35]
	s_mov_b32 m0, s76
	ds_read_b128 v[230:233], v180 offset:23552
	global_load_lds_dwordx4 v138, s[74:75]
	s_add_i32 m0, s76, 0x2000
	ds_read_b128 v[226:229], v180 offset:22528
	global_load_lds_dwordx4 v142, s[74:75]
	s_mov_b32 m0, s46
	ds_read_b128 v[222:225], v180 offset:21504
	global_load_lds_dwordx4 v136, s[36:37]
	s_mov_b32 m0, s47
	ds_read_b128 v[218:221], v180 offset:20480
	global_load_lds_dwordx4 v140, s[36:37]
	s_waitcnt vmcnt(10) lgkmcnt(0)
	s_barrier
	s_setprio 1
	v_mfma_i32_16x16x64_i8 v[68:71], v[160:163], v[202:205], v[68:71]
	v_mfma_i32_16x16x64_i8 v[64:67], v[168:171], v[202:205], v[64:67]
	v_mfma_i32_16x16x64_i8 v[60:63], v[160:163], v[210:213], v[60:63]
	v_mfma_i32_16x16x64_i8 v[56:59], v[168:171], v[210:213], v[56:59]
	v_mfma_i32_16x16x64_i8 v[48:51], v[160:163], v[218:221], v[48:51]
	v_mfma_i32_16x16x64_i8 v[40:43], v[168:171], v[218:221], v[40:43]
	v_mfma_i32_16x16x64_i8 v[32:35], v[160:163], v[226:229], v[32:35]
	v_mfma_i32_16x16x64_i8 v[24:27], v[168:171], v[226:229], v[24:27]
	v_mfma_i32_16x16x64_i8 v[68:71], v[164:167], v[206:209], v[68:71]
	v_mfma_i32_16x16x64_i8 v[64:67], v[182:185], v[206:209], v[64:67]
	v_mfma_i32_16x16x64_i8 v[60:63], v[164:167], v[214:217], v[60:63]
	v_mfma_i32_16x16x64_i8 v[56:59], v[182:185], v[214:217], v[56:59]
	v_mfma_i32_16x16x64_i8 v[48:51], v[164:167], v[222:225], v[48:51]
	v_mfma_i32_16x16x64_i8 v[40:43], v[182:185], v[222:225], v[40:43]
	v_mfma_i32_16x16x64_i8 v[32:35], v[164:167], v[230:233], v[32:35]
	v_mfma_i32_16x16x64_i8 v[24:27], v[182:185], v[230:233], v[24:27]
	s_setprio 0
	s_setprio 1
	v_mfma_i32_16x16x64_i8 v[52:55], v[186:189], v[202:205], v[52:55]
	v_mfma_i32_16x16x64_i8 v[44:47], v[194:197], v[202:205], v[44:47]
	v_mfma_i32_16x16x64_i8 v[36:39], v[186:189], v[210:213], v[36:39]
	v_mfma_i32_16x16x64_i8 v[28:31], v[194:197], v[210:213], v[28:31]
	v_mfma_i32_16x16x64_i8 v[20:23], v[186:189], v[218:221], v[20:23]
	v_mfma_i32_16x16x64_i8 v[16:19], v[194:197], v[218:221], v[16:19]
	v_mfma_i32_16x16x64_i8 v[12:15], v[186:189], v[226:229], v[12:15]
	v_mfma_i32_16x16x64_i8 v[6:9], v[194:197], v[226:229], v[8:11]
	v_mfma_i32_16x16x64_i8 v[52:55], v[190:193], v[206:209], v[52:55]
	v_mfma_i32_16x16x64_i8 v[44:47], v[198:201], v[206:209], v[44:47]
	v_mfma_i32_16x16x64_i8 v[36:39], v[190:193], v[214:217], v[36:39]
	v_mfma_i32_16x16x64_i8 v[28:31], v[198:201], v[214:217], v[28:31]
	v_mfma_i32_16x16x64_i8 v[20:23], v[190:193], v[222:225], v[20:23]
	v_mfma_i32_16x16x64_i8 v[16:19], v[198:201], v[222:225], v[16:19]
	v_mfma_i32_16x16x64_i8 v[12:15], v[190:193], v[230:233], v[12:15]
	v_mfma_i32_16x16x64_i8 v[6:9], v[198:201], v[230:233], v[6:9]
	s_setprio 0
	s_barrier
	s_add_i32 s74, 0, 0x18000
	s_add_i32 s75, 0, 0x1c000
	ds_read_b128 v[160:163], v177 offset:32768
	ds_read_b128 v[164:167], v177 offset:33792
	ds_read_b128 v[168:171], v177 offset:34816
	ds_read_b128 v[182:185], v177 offset:35840
	ds_read_b128 v[186:189], v177 offset:49152
	ds_read_b128 v[190:193], v177 offset:50176
	ds_read_b128 v[194:197], v177 offset:51200
	ds_read_b128 v[198:201], v177 offset:52224
	s_add_u32 s36, s36, 0x80000
	s_addc_u32 s37, s37, 0
	s_mov_b32 m0, s48
	ds_read_b128 v[202:205], v180 offset:32768
	ds_read_b128 v[206:209], v180 offset:33792
	ds_read_b128 v[210:213], v180 offset:34816
	ds_read_b128 v[214:217], v180 offset:35840
	ds_read_b128 v[218:221], v180 offset:36864
	ds_read_b128 v[222:225], v180 offset:37888
	ds_read_b128 v[226:229], v180 offset:38912
	global_load_lds_dwordx4 v136, s[36:37]
	s_mov_b32 m0, s49
	ds_read_b128 v[230:233], v180 offset:39936
	global_load_lds_dwordx4 v140, s[36:37]
	s_waitcnt vmcnt(8) lgkmcnt(0)
	s_barrier
	s_setprio 1
	v_mfma_i32_16x16x64_i8 v[132:135], v[160:163], v[202:205], v[132:135]
	v_mfma_i32_16x16x64_i8 v[128:131], v[168:171], v[202:205], v[128:131]
	v_mfma_i32_16x16x64_i8 v[124:127], v[160:163], v[210:213], v[124:127]
	v_mfma_i32_16x16x64_i8 v[120:123], v[168:171], v[210:213], v[120:123]
	v_mfma_i32_16x16x64_i8 v[112:115], v[160:163], v[218:221], v[112:115]
	v_max3_f32 v0, v0, |v152|, |v156|
	v_mfma_i32_16x16x64_i8 v[104:107], v[168:171], v[218:221], v[104:107]
	v_max3_f32 v1, v1, |v153|, |v157|
	v_mfma_i32_16x16x64_i8 v[96:99], v[160:163], v[226:229], v[96:99]
	v_max3_f32 v2, v2, |v154|, |v158|
	v_mfma_i32_16x16x64_i8 v[88:91], v[168:171], v[226:229], v[88:91]
	v_max3_f32 v3, v3, |v155|, |v159|
	v_mfma_i32_16x16x64_i8 v[132:135], v[164:167], v[206:209], v[132:135]
	v_mfma_i32_16x16x64_i8 v[128:131], v[182:185], v[206:209], v[128:131]
	v_mfma_i32_16x16x64_i8 v[124:127], v[164:167], v[214:217], v[124:127]
	v_mfma_i32_16x16x64_i8 v[120:123], v[182:185], v[214:217], v[120:123]
	v_mfma_i32_16x16x64_i8 v[112:115], v[164:167], v[222:225], v[112:115]
	v_mfma_i32_16x16x64_i8 v[104:107], v[182:185], v[222:225], v[104:107]
	v_mfma_i32_16x16x64_i8 v[96:99], v[164:167], v[230:233], v[96:99]
	v_mfma_i32_16x16x64_i8 v[88:91], v[182:185], v[230:233], v[88:91]
	s_setprio 0
	s_setprio 1
	v_mfma_i32_16x16x64_i8 v[116:119], v[186:189], v[202:205], v[116:119]
	v_mfma_i32_16x16x64_i8 v[108:111], v[194:197], v[202:205], v[108:111]
	v_mfma_i32_16x16x64_i8 v[100:103], v[186:189], v[210:213], v[100:103]
	v_mfma_i32_16x16x64_i8 v[92:95], v[194:197], v[210:213], v[92:95]
	v_mfma_i32_16x16x64_i8 v[84:87], v[186:189], v[218:221], v[84:87]
	v_mfma_i32_16x16x64_i8 v[80:83], v[194:197], v[218:221], v[80:83]
	v_mfma_i32_16x16x64_i8 v[76:79], v[186:189], v[226:229], v[76:79]
	v_mfma_i32_16x16x64_i8 v[72:75], v[194:197], v[226:229], v[72:75]
	v_mfma_i32_16x16x64_i8 v[116:119], v[190:193], v[206:209], v[116:119]
	v_mfma_i32_16x16x64_i8 v[108:111], v[198:201], v[206:209], v[108:111]
	v_mfma_i32_16x16x64_i8 v[100:103], v[190:193], v[214:217], v[100:103]
	v_mfma_i32_16x16x64_i8 v[92:95], v[198:201], v[214:217], v[92:95]
	v_mfma_i32_16x16x64_i8 v[84:87], v[190:193], v[222:225], v[84:87]
	v_mfma_i32_16x16x64_i8 v[80:83], v[198:201], v[222:225], v[80:83]
	v_mfma_i32_16x16x64_i8 v[76:79], v[190:193], v[230:233], v[76:79]
	v_mfma_i32_16x16x64_i8 v[72:75], v[198:201], v[230:233], v[72:75]
	s_setprio 0
	s_barrier
	s_add_u32 s98, s34, s14
	s_addc_u32 s99, s35, s15
	s_add_u32 s100, s36, s14
	s_addc_u32 s101, s37, s15
	s_sub_u32 s100, s100, 0x80000
	s_subb_u32 s101, s101, 0
	s_add_i32 s36, s74, s45
	s_mov_b32 m0, s36
	ds_read_b128 v[152:155], v180 offset:49152
	ds_read_b128 v[156:159], v180 offset:50176
	ds_read_b128 v[202:205], v180 offset:51200
	ds_read_b128 v[206:209], v180 offset:52224
	global_load_lds_dwordx4 v138, s[98:99]
	s_add_i32 m0, s36, 0x2000
	s_add_u32 s34, s34, 0x80080
	s_addc_u32 s35, s35, 0
	s_add_i32 s36, s75, s45
	global_load_lds_dwordx4 v142, s[98:99]
	s_mov_b32 m0, s36
	ds_read_b128 v[222:225], v180 offset:56320
	global_load_lds_dwordx4 v138, s[34:35]
	s_add_i32 m0, s36, 0x2000
	ds_read_b128 v[218:221], v180 offset:55296
	global_load_lds_dwordx4 v142, s[34:35]
	s_mov_b32 m0, s54
	ds_read_b128 v[214:217], v180 offset:54272
	global_load_lds_dwordx4 v136, s[100:101]
	s_mov_b32 m0, s55
	ds_read_b128 v[210:213], v180 offset:53248
	global_load_lds_dwordx4 v140, s[100:101]
	s_waitcnt vmcnt(8) lgkmcnt(0)
	s_barrier
	s_setprio 1
	v_mfma_i32_16x16x64_i8 v[68:71], v[160:163], v[152:155], v[68:71]
	v_mfma_i32_16x16x64_i8 v[64:67], v[168:171], v[152:155], v[64:67]
	v_mfma_i32_16x16x64_i8 v[60:63], v[160:163], v[202:205], v[60:63]
	v_mfma_i32_16x16x64_i8 v[56:59], v[168:171], v[202:205], v[56:59]
	v_mfma_i32_16x16x64_i8 v[48:51], v[160:163], v[210:213], v[48:51]
	v_mfma_i32_16x16x64_i8 v[40:43], v[168:171], v[210:213], v[40:43]
	v_mfma_i32_16x16x64_i8 v[32:35], v[160:163], v[218:221], v[32:35]
	v_mfma_i32_16x16x64_i8 v[24:27], v[168:171], v[218:221], v[24:27]
	v_mfma_i32_16x16x64_i8 v[68:71], v[164:167], v[156:159], v[68:71]
	v_mfma_i32_16x16x64_i8 v[64:67], v[182:185], v[156:159], v[64:67]
	v_mfma_i32_16x16x64_i8 v[60:63], v[164:167], v[206:209], v[60:63]
	v_mfma_i32_16x16x64_i8 v[56:59], v[182:185], v[206:209], v[56:59]
	v_mfma_i32_16x16x64_i8 v[48:51], v[164:167], v[214:217], v[48:51]
	v_mfma_i32_16x16x64_i8 v[40:43], v[182:185], v[214:217], v[40:43]
	v_mfma_i32_16x16x64_i8 v[32:35], v[164:167], v[222:225], v[32:35]
	v_mfma_i32_16x16x64_i8 v[24:27], v[182:185], v[222:225], v[24:27]
	s_setprio 0
	s_setprio 1
	v_mfma_i32_16x16x64_i8 v[52:55], v[186:189], v[152:155], v[52:55]
	v_mfma_i32_16x16x64_i8 v[44:47], v[194:197], v[152:155], v[44:47]
	v_mfma_i32_16x16x64_i8 v[36:39], v[186:189], v[202:205], v[36:39]
	v_mfma_i32_16x16x64_i8 v[28:31], v[194:197], v[202:205], v[28:31]
	v_mfma_i32_16x16x64_i8 v[20:23], v[186:189], v[210:213], v[20:23]
	v_mfma_i32_16x16x64_i8 v[16:19], v[194:197], v[210:213], v[16:19]
	v_mfma_i32_16x16x64_i8 v[10:13], v[186:189], v[218:221], v[12:15]
	v_mfma_i32_16x16x64_i8 v[6:9], v[194:197], v[218:221], v[6:9]
	v_mfma_i32_16x16x64_i8 v[52:55], v[190:193], v[156:159], v[52:55]
	v_mfma_i32_16x16x64_i8 v[44:47], v[198:201], v[156:159], v[44:47]
	v_mfma_i32_16x16x64_i8 v[36:39], v[190:193], v[206:209], v[36:39]
	v_mfma_i32_16x16x64_i8 v[28:31], v[198:201], v[206:209], v[28:31]
	v_mfma_i32_16x16x64_i8 v[20:23], v[190:193], v[214:217], v[20:23]
	v_mfma_i32_16x16x64_i8 v[16:19], v[198:201], v[214:217], v[16:19]
	v_mfma_i32_16x16x64_i8 v[12:15], v[190:193], v[222:225], v[10:13]
	v_mfma_i32_16x16x64_i8 v[8:11], v[198:201], v[222:225], v[6:9]
	s_setprio 0
	s_barrier
	s_add_u32 s30, s30, 0x100
	s_addc_u32 s31, s31, 0
	s_add_u32 s72, s72, 0x100
	s_addc_u32 s73, s73, 0
	s_cmp_ge_i32 s8, s66
	s_cbranch_scc0 .LBB0_312

.Lp4_body:
	s_add_i32 s8, s71, 2
	s_add_u32 s28, s26, 0xfff00080
	s_addc_u32 s29, s27, -1
	s_cmp_eq_u32 s68, s71
	s_cselect_b32 s31, s64, s29
	s_cselect_b32 s30, s65, s28
	s_cselect_b32 s29, s66, s70
	s_cselect_b32 s28, s67, s69
	ds_read_b128 v[172:175], v163
	ds_read_b128 v[176:179], v163 offset:1024
	ds_read_b128 v[180:183], v163 offset:2048
	ds_read_b128 v[184:187], v163 offset:3072
	ds_read_b128 v[188:191], v163 offset:16384
	ds_read_b128 v[192:195], v163 offset:17408
	ds_read_b128 v[196:199], v163 offset:18432
	ds_read_b128 v[200:203], v163 offset:19456
	s_add_i32 m0, s43, 0xc000
	ds_read_b128 v[204:207], v166
	ds_read_b128 v[208:211], v166 offset:1024
	ds_read_b128 v[212:215], v166 offset:2048
	ds_read_b128 v[216:219], v166 offset:3072
	ds_read_b128 v[220:223], v166 offset:4096
	ds_read_b128 v[224:227], v166 offset:5120
	ds_read_b128 v[236:239], v166 offset:6144
	global_load_lds_dwordx4 v146, s[26:27]
	s_add_i32 m0, s43, 0xe000
	ds_read_b128 v[240:243], v166 offset:7168
	global_load_lds_dwordx4 v148, s[26:27]
	s_waitcnt vmcnt(8) lgkmcnt(0)
	s_barrier
	s_setprio 1
	v_mfma_f32_16x16x32_bf16 v[132:135], v[172:175], v[204:207], v[132:135]
	v_mfma_f32_16x16x32_bf16 v[128:131], v[180:183], v[204:207], v[128:131]
	v_mfma_f32_16x16x32_bf16 v[116:119], v[172:175], v[212:215], v[116:119]
	v_mfma_f32_16x16x32_bf16 v[112:115], v[180:183], v[212:215], v[112:115]
	v_mfma_f32_16x16x32_bf16 v[100:103], v[172:175], v[220:223], v[100:103]
	v_mfma_f32_16x16x32_bf16 v[96:99], v[180:183], v[220:223], v[96:99]
	v_mfma_f32_16x16x32_bf16 v[84:87], v[172:175], v[236:239], v[84:87]
	v_mfma_f32_16x16x32_bf16 v[80:83], v[180:183], v[236:239], v[80:83]
	v_mfma_f32_16x16x32_bf16 v[132:135], v[176:179], v[208:211], v[132:135]
	v_mfma_f32_16x16x32_bf16 v[128:131], v[184:187], v[208:211], v[128:131]
	v_mfma_f32_16x16x32_bf16 v[116:119], v[176:179], v[216:219], v[116:119]
	v_mfma_f32_16x16x32_bf16 v[112:115], v[184:187], v[216:219], v[112:115]
	v_mfma_f32_16x16x32_bf16 v[100:103], v[176:179], v[224:227], v[100:103]
	v_mfma_f32_16x16x32_bf16 v[96:99], v[184:187], v[224:227], v[96:99]
	v_mfma_f32_16x16x32_bf16 v[84:87], v[176:179], v[240:243], v[84:87]
	v_mfma_f32_16x16x32_bf16 v[80:83], v[184:187], v[240:243], v[80:83]
	s_setprio 0
	s_setprio 1
	v_mfma_f32_16x16x32_bf16 v[124:127], v[188:191], v[204:207], v[124:127]
	v_mfma_f32_16x16x32_bf16 v[120:123], v[196:199], v[204:207], v[120:123]
	v_mfma_f32_16x16x32_bf16 v[108:111], v[188:191], v[212:215], v[108:111]
	v_mfma_f32_16x16x32_bf16 v[104:107], v[196:199], v[212:215], v[104:107]
	v_mfma_f32_16x16x32_bf16 v[92:95], v[188:191], v[220:223], v[92:95]
	v_mfma_f32_16x16x32_bf16 v[88:91], v[196:199], v[220:223], v[88:91]
	v_mfma_f32_16x16x32_bf16 v[76:79], v[188:191], v[236:239], v[76:79]
	v_mfma_f32_16x16x32_bf16 v[72:75], v[196:199], v[236:239], v[72:75]
	v_mfma_f32_16x16x32_bf16 v[124:127], v[192:195], v[208:211], v[124:127]
	v_mfma_f32_16x16x32_bf16 v[120:123], v[200:203], v[208:211], v[120:123]
	v_mfma_f32_16x16x32_bf16 v[108:111], v[192:195], v[216:219], v[108:111]
	v_mfma_f32_16x16x32_bf16 v[104:107], v[200:203], v[216:219], v[104:107]
	v_mfma_f32_16x16x32_bf16 v[92:95], v[192:195], v[224:227], v[92:95]
	v_mfma_f32_16x16x32_bf16 v[88:91], v[200:203], v[224:227], v[88:91]
	v_mfma_f32_16x16x32_bf16 v[76:79], v[192:195], v[240:243], v[76:79]
	v_mfma_f32_16x16x32_bf16 v[72:75], v[200:203], v[240:243], v[72:75]
	s_setprio 0
	s_barrier
	s_add_i32 s71, s53, s40
	s_mov_b32 m0, s71
	ds_read_b128 v[204:207], v166 offset:16384
	ds_read_b128 v[208:211], v166 offset:17408
	ds_read_b128 v[212:215], v166 offset:18432
	ds_read_b128 v[216:219], v166 offset:19456
	global_load_lds_dwordx4 v138, s[28:29]
	s_add_i32 m0, s71, 0x2000
	s_add_u32 s72, s28, 0x100000
	s_addc_u32 s73, s29, 0
	s_add_i32 s71, s54, s40
	global_load_lds_dwordx4 v142, s[28:29]
	s_mov_b32 m0, s71
	ds_read_b128 v[240:243], v166 offset:23552
	global_load_lds_dwordx4 v138, s[72:73]
	s_add_i32 m0, s71, 0x2000
	ds_read_b128 v[236:239], v166 offset:22528
	global_load_lds_dwordx4 v142, s[72:73]
	s_mov_b32 m0, s43
	ds_read_b128 v[224:227], v166 offset:21504
	global_load_lds_dwordx4 v136, s[30:31]
	s_mov_b32 m0, s44
	ds_read_b128 v[220:223], v166 offset:20480
	global_load_lds_dwordx4 v140, s[30:31]
	s_waitcnt vmcnt(8) lgkmcnt(0)
	s_barrier
	s_setprio 1
	v_mfma_f32_16x16x32_bf16 v[68:71], v[172:175], v[204:207], v[68:71]
	v_mfma_f32_16x16x32_bf16 v[64:67], v[180:183], v[204:207], v[64:67]
	v_mfma_f32_16x16x32_bf16 v[52:55], v[172:175], v[212:215], v[52:55]
	v_mfma_f32_16x16x32_bf16 v[48:51], v[180:183], v[212:215], v[48:51]
	v_mfma_f32_16x16x32_bf16 v[36:39], v[172:175], v[220:223], v[36:39]
	v_mfma_f32_16x16x32_bf16 v[32:35], v[180:183], v[220:223], v[32:35]
	v_mfma_f32_16x16x32_bf16 v[20:23], v[172:175], v[236:239], v[20:23]
	v_mfma_f32_16x16x32_bf16 v[16:19], v[180:183], v[236:239], v[16:19]
	v_mfma_f32_16x16x32_bf16 v[68:71], v[176:179], v[208:211], v[68:71]
	v_mfma_f32_16x16x32_bf16 v[64:67], v[184:187], v[208:211], v[64:67]
	v_mfma_f32_16x16x32_bf16 v[52:55], v[176:179], v[216:219], v[52:55]
	v_mfma_f32_16x16x32_bf16 v[48:51], v[184:187], v[216:219], v[48:51]
	v_mfma_f32_16x16x32_bf16 v[36:39], v[176:179], v[224:227], v[36:39]
	v_mfma_f32_16x16x32_bf16 v[32:35], v[184:187], v[224:227], v[32:35]
	v_mfma_f32_16x16x32_bf16 v[20:23], v[176:179], v[240:243], v[20:23]
	v_mfma_f32_16x16x32_bf16 v[16:19], v[184:187], v[240:243], v[16:19]
	s_setprio 0
	s_setprio 1
	v_mfma_f32_16x16x32_bf16 v[60:63], v[188:191], v[204:207], v[60:63]
	v_mfma_f32_16x16x32_bf16 v[56:59], v[196:199], v[204:207], v[56:59]
	v_mfma_f32_16x16x32_bf16 v[44:47], v[188:191], v[212:215], v[44:47]
	v_mfma_f32_16x16x32_bf16 v[40:43], v[196:199], v[212:215], v[40:43]
	v_mfma_f32_16x16x32_bf16 v[28:31], v[188:191], v[220:223], v[28:31]
	v_mfma_f32_16x16x32_bf16 v[24:27], v[196:199], v[220:223], v[24:27]
	v_mfma_f32_16x16x32_bf16 v[12:15], v[188:191], v[236:239], v[12:15]
	v_mfma_f32_16x16x32_bf16 v[6:9], v[196:199], v[236:239], v[8:11]
	v_mfma_f32_16x16x32_bf16 v[60:63], v[192:195], v[208:211], v[60:63]
	v_mfma_f32_16x16x32_bf16 v[56:59], v[200:203], v[208:211], v[56:59]
	v_mfma_f32_16x16x32_bf16 v[44:47], v[192:195], v[216:219], v[44:47]
	v_mfma_f32_16x16x32_bf16 v[40:43], v[200:203], v[216:219], v[40:43]
	v_mfma_f32_16x16x32_bf16 v[28:31], v[192:195], v[224:227], v[28:31]
	v_mfma_f32_16x16x32_bf16 v[24:27], v[200:203], v[224:227], v[24:27]
	v_mfma_f32_16x16x32_bf16 v[12:15], v[192:195], v[240:243], v[12:15]
	v_mfma_f32_16x16x32_bf16 v[6:9], v[200:203], v[240:243], v[6:9]
	s_setprio 0
	s_barrier
	s_add_i32 s71, 0, 0x18000
	s_add_i32 s72, 0, 0x1c000
	ds_read_b128 v[172:175], v163 offset:32768
	ds_read_b128 v[176:179], v163 offset:33792
	ds_read_b128 v[180:183], v163 offset:34816
	ds_read_b128 v[184:187], v163 offset:35840
	ds_read_b128 v[188:191], v163 offset:49152
	ds_read_b128 v[192:195], v163 offset:50176
	ds_read_b128 v[196:199], v163 offset:51200
	ds_read_b128 v[200:203], v163 offset:52224
	s_add_u32 s30, s30, 0x100000
	s_addc_u32 s31, s31, 0
	s_mov_b32 m0, s45
	ds_read_b128 v[204:207], v166 offset:32768
	ds_read_b128 v[208:211], v166 offset:33792
	ds_read_b128 v[212:215], v166 offset:34816
	ds_read_b128 v[216:219], v166 offset:35840
	ds_read_b128 v[220:223], v166 offset:36864
	ds_read_b128 v[224:227], v166 offset:37888
	ds_read_b128 v[236:239], v166 offset:38912
	global_load_lds_dwordx4 v136, s[30:31]
	s_mov_b32 m0, s46
	ds_read_b128 v[240:243], v166 offset:39936
	global_load_lds_dwordx4 v140, s[30:31]
	s_waitcnt vmcnt(8) lgkmcnt(0)
	s_barrier
	s_setprio 1
	v_mfma_f32_16x16x32_bf16 v[132:135], v[172:175], v[204:207], v[132:135]
	v_mfma_f32_16x16x32_bf16 v[128:131], v[180:183], v[204:207], v[128:131]
	v_mfma_f32_16x16x32_bf16 v[116:119], v[172:175], v[212:215], v[116:119]
	v_mfma_f32_16x16x32_bf16 v[112:115], v[180:183], v[212:215], v[112:115]
	v_mfma_f32_16x16x32_bf16 v[100:103], v[172:175], v[220:223], v[100:103]
	v_mfma_f32_16x16x32_bf16 v[96:99], v[180:183], v[220:223], v[96:99]
	v_mfma_f32_16x16x32_bf16 v[84:87], v[172:175], v[236:239], v[84:87]
	v_mfma_f32_16x16x32_bf16 v[80:83], v[180:183], v[236:239], v[80:83]
	v_mfma_f32_16x16x32_bf16 v[132:135], v[176:179], v[208:211], v[132:135]
	v_mfma_f32_16x16x32_bf16 v[128:131], v[184:187], v[208:211], v[128:131]
	v_mfma_f32_16x16x32_bf16 v[116:119], v[176:179], v[216:219], v[116:119]
	v_mfma_f32_16x16x32_bf16 v[112:115], v[184:187], v[216:219], v[112:115]
	v_mfma_f32_16x16x32_bf16 v[100:103], v[176:179], v[224:227], v[100:103]
	v_mfma_f32_16x16x32_bf16 v[96:99], v[184:187], v[224:227], v[96:99]
	v_mfma_f32_16x16x32_bf16 v[84:87], v[176:179], v[240:243], v[84:87]
	v_mfma_f32_16x16x32_bf16 v[80:83], v[184:187], v[240:243], v[80:83]
	s_setprio 0
	s_setprio 1
	v_mfma_f32_16x16x32_bf16 v[124:127], v[188:191], v[204:207], v[124:127]
	v_mfma_f32_16x16x32_bf16 v[120:123], v[196:199], v[204:207], v[120:123]
	v_mfma_f32_16x16x32_bf16 v[108:111], v[188:191], v[212:215], v[108:111]
	v_mfma_f32_16x16x32_bf16 v[104:107], v[196:199], v[212:215], v[104:107]
	v_mfma_f32_16x16x32_bf16 v[92:95], v[188:191], v[220:223], v[92:95]
	v_mfma_f32_16x16x32_bf16 v[88:91], v[196:199], v[220:223], v[88:91]
	v_mfma_f32_16x16x32_bf16 v[76:79], v[188:191], v[236:239], v[76:79]
	v_mfma_f32_16x16x32_bf16 v[72:75], v[196:199], v[236:239], v[72:75]
	v_mfma_f32_16x16x32_bf16 v[124:127], v[192:195], v[208:211], v[124:127]
	v_mfma_f32_16x16x32_bf16 v[120:123], v[200:203], v[208:211], v[120:123]
	v_mfma_f32_16x16x32_bf16 v[108:111], v[192:195], v[216:219], v[108:111]
	v_mfma_f32_16x16x32_bf16 v[104:107], v[200:203], v[216:219], v[104:107]
	v_mfma_f32_16x16x32_bf16 v[92:95], v[192:195], v[224:227], v[92:95]
	v_mfma_f32_16x16x32_bf16 v[88:91], v[200:203], v[224:227], v[88:91]
	v_mfma_f32_16x16x32_bf16 v[76:79], v[192:195], v[240:243], v[76:79]
	v_mfma_f32_16x16x32_bf16 v[72:75], v[200:203], v[240:243], v[72:75]
	s_setprio 0
	s_barrier
	s_add_u32 s74, s28, s6
	s_addc_u32 s75, s29, s7
	s_add_u32 s76, s30, s6
	s_addc_u32 s77, s31, s7
	s_sub_u32 s76, s76, 0x100000
	s_subb_u32 s77, s77, 0
	s_add_i32 s30, s71, s40
	s_mov_b32 m0, s30
	ds_read_b128 v[152:155], v166 offset:49152
	ds_read_b128 v[168:171], v166 offset:50176
	ds_read_b128 v[204:207], v166 offset:51200
	ds_read_b128 v[208:211], v166 offset:52224
	global_load_lds_dwordx4 v138, s[74:75]
	s_add_i32 m0, s30, 0x2000
	s_add_u32 s28, s28, 0x100080
	s_addc_u32 s29, s29, 0
	s_add_i32 s30, s72, s40
	global_load_lds_dwordx4 v142, s[74:75]
	s_mov_b32 m0, s30
	ds_read_b128 v[224:227], v166 offset:56320
	global_load_lds_dwordx4 v138, s[28:29]
	s_add_i32 m0, s30, 0x2000
	ds_read_b128 v[220:223], v166 offset:55296
	global_load_lds_dwordx4 v142, s[28:29]
	s_mov_b32 m0, s49
	ds_read_b128 v[216:219], v166 offset:54272
	global_load_lds_dwordx4 v136, s[76:77]
	s_mov_b32 m0, s50
	ds_read_b128 v[212:215], v166 offset:53248
	global_load_lds_dwordx4 v140, s[76:77]
	s_waitcnt vmcnt(8) lgkmcnt(0)
	s_barrier
	s_setprio 1
	v_mfma_f32_16x16x32_bf16 v[68:71], v[172:175], v[152:155], v[68:71]
	v_mfma_f32_16x16x32_bf16 v[64:67], v[180:183], v[152:155], v[64:67]
	v_mfma_f32_16x16x32_bf16 v[52:55], v[172:175], v[204:207], v[52:55]
	v_mfma_f32_16x16x32_bf16 v[48:51], v[180:183], v[204:207], v[48:51]
	v_mfma_f32_16x16x32_bf16 v[36:39], v[172:175], v[212:215], v[36:39]
	v_mfma_f32_16x16x32_bf16 v[32:35], v[180:183], v[212:215], v[32:35]
	v_mfma_f32_16x16x32_bf16 v[20:23], v[172:175], v[220:223], v[20:23]
	v_mfma_f32_16x16x32_bf16 v[16:19], v[180:183], v[220:223], v[16:19]
	v_mfma_f32_16x16x32_bf16 v[68:71], v[176:179], v[168:171], v[68:71]
	v_mfma_f32_16x16x32_bf16 v[64:67], v[184:187], v[168:171], v[64:67]
	v_mfma_f32_16x16x32_bf16 v[52:55], v[176:179], v[208:211], v[52:55]
	v_mfma_f32_16x16x32_bf16 v[48:51], v[184:187], v[208:211], v[48:51]
	v_mfma_f32_16x16x32_bf16 v[36:39], v[176:179], v[216:219], v[36:39]
	v_mfma_f32_16x16x32_bf16 v[32:35], v[184:187], v[216:219], v[32:35]
	v_mfma_f32_16x16x32_bf16 v[20:23], v[176:179], v[224:227], v[20:23]
	v_mfma_f32_16x16x32_bf16 v[16:19], v[184:187], v[224:227], v[16:19]
	s_setprio 0
	s_setprio 1
	v_mfma_f32_16x16x32_bf16 v[60:63], v[188:191], v[152:155], v[60:63]
	v_mfma_f32_16x16x32_bf16 v[56:59], v[196:199], v[152:155], v[56:59]
	v_mfma_f32_16x16x32_bf16 v[44:47], v[188:191], v[204:207], v[44:47]
	v_mfma_f32_16x16x32_bf16 v[40:43], v[196:199], v[204:207], v[40:43]
	v_mfma_f32_16x16x32_bf16 v[28:31], v[188:191], v[212:215], v[28:31]
	v_mfma_f32_16x16x32_bf16 v[24:27], v[196:199], v[212:215], v[24:27]
	v_mfma_f32_16x16x32_bf16 v[10:13], v[188:191], v[220:223], v[12:15]
	v_mfma_f32_16x16x32_bf16 v[6:9], v[196:199], v[220:223], v[6:9]
	v_mfma_f32_16x16x32_bf16 v[60:63], v[192:195], v[168:171], v[60:63]
	v_mfma_f32_16x16x32_bf16 v[56:59], v[200:203], v[168:171], v[56:59]
	v_mfma_f32_16x16x32_bf16 v[44:47], v[192:195], v[208:211], v[44:47]
	v_mfma_f32_16x16x32_bf16 v[40:43], v[200:203], v[208:211], v[40:43]
	v_mfma_f32_16x16x32_bf16 v[28:31], v[192:195], v[216:219], v[28:31]
	v_mfma_f32_16x16x32_bf16 v[24:27], v[200:203], v[216:219], v[24:27]
	v_mfma_f32_16x16x32_bf16 v[12:15], v[192:195], v[224:227], v[10:13]
	v_mfma_f32_16x16x32_bf16 v[8:11], v[200:203], v[224:227], v[6:9]
	s_setprio 0
	s_barrier
	s_add_u32 s26, s26, 0x100
	s_addc_u32 s27, s27, 0
	s_add_u32 s69, s69, 0x100
	s_addc_u32 s70, s70, 0
	s_cmp_ge_i32 s8, s63
	s_cbranch_scc0 .Lp4_top
	s_branch .Lp4_epi

.LBB0_1033:
	s_add_i32 s8, s71, 2
	s_add_u32 s28, s26, 0xfff00080
	s_addc_u32 s29, s27, -1
	s_cmp_eq_u32 s68, s71
	s_cselect_b32 s31, s64, s29
	s_cselect_b32 s30, s65, s28
	s_cselect_b32 s29, s66, s70
	s_cselect_b32 s28, s67, s69
	s_cmpk_lt_i32 s3, 0x56
	s_cselect_b32 s71, s52, 0x2b00
	s_mov_b32 s72, 0xac00
	s_cselect_b32 s74, s72, 0x4000
	s_sub_i32 s71, s71, s33
	v_min3_i32 v5, s71, v160, 2
	v_sub_u32_e32 v160, v160, v5
	v_readfirstlane_b32 s71, v5
	s_max_i32 s72, s71, 0
	s_add_i32 s72, s33, s72
	s_add_i32 s75, s72, -1
	s_min_i32 s72, s33, s75
	s_mul_hi_i32 s73, s74, s72
	s_mul_i32 s72, s74, s72
	s_add_u32 s72, s34, s72
	s_addc_u32 s73, s35, s73
	s_mul_hi_i32 s76, s74, s75
	s_mul_i32 s74, s74, s75
	s_add_u32 s74, s34, s74
	global_load_dwordx4 v[152:155], v159, s[72:73] nt
	s_addc_u32 s75, s35, s76
	global_load_dwordx4 v[168:171], v159, s[74:75] nt
	s_add_i32 s33, s71, s33
	ds_read_b128 v[172:175], v163
	ds_read_b128 v[176:179], v163 offset:1024
	ds_read_b128 v[180:183], v163 offset:2048
	ds_read_b128 v[184:187], v163 offset:3072
	ds_read_b128 v[188:191], v163 offset:16384
	ds_read_b128 v[192:195], v163 offset:17408
	ds_read_b128 v[196:199], v163 offset:18432
	ds_read_b128 v[200:203], v163 offset:19456
	s_add_i32 m0, s43, 0xc000
	ds_read_b128 v[204:207], v166
	ds_read_b128 v[208:211], v166 offset:1024
	ds_read_b128 v[212:215], v166 offset:2048
	ds_read_b128 v[216:219], v166 offset:3072
	ds_read_b128 v[220:223], v166 offset:4096
	ds_read_b128 v[224:227], v166 offset:5120
	ds_read_b128 v[236:239], v166 offset:6144
	global_load_lds_dwordx4 v146, s[26:27]
	s_add_i32 m0, s43, 0xe000
	ds_read_b128 v[240:243], v166 offset:7168
	global_load_lds_dwordx4 v148, s[26:27]
	s_waitcnt vmcnt(10) lgkmcnt(0)
	s_barrier
	s_setprio 1
	v_mfma_f32_16x16x32_bf16 v[132:135], v[172:175], v[204:207], v[132:135]
	v_mfma_f32_16x16x32_bf16 v[128:131], v[180:183], v[204:207], v[128:131]
	v_mfma_f32_16x16x32_bf16 v[116:119], v[172:175], v[212:215], v[116:119]
	v_mfma_f32_16x16x32_bf16 v[112:115], v[180:183], v[212:215], v[112:115]
	v_mfma_f32_16x16x32_bf16 v[100:103], v[172:175], v[220:223], v[100:103]
	v_mfma_f32_16x16x32_bf16 v[96:99], v[180:183], v[220:223], v[96:99]
	v_mfma_f32_16x16x32_bf16 v[84:87], v[172:175], v[236:239], v[84:87]
	v_mfma_f32_16x16x32_bf16 v[80:83], v[180:183], v[236:239], v[80:83]
	v_mfma_f32_16x16x32_bf16 v[132:135], v[176:179], v[208:211], v[132:135]
	v_mfma_f32_16x16x32_bf16 v[128:131], v[184:187], v[208:211], v[128:131]
	v_mfma_f32_16x16x32_bf16 v[116:119], v[176:179], v[216:219], v[116:119]
	v_mfma_f32_16x16x32_bf16 v[112:115], v[184:187], v[216:219], v[112:115]
	v_mfma_f32_16x16x32_bf16 v[100:103], v[176:179], v[224:227], v[100:103]
	v_mfma_f32_16x16x32_bf16 v[96:99], v[184:187], v[224:227], v[96:99]
	v_mfma_f32_16x16x32_bf16 v[84:87], v[176:179], v[240:243], v[84:87]
	v_mfma_f32_16x16x32_bf16 v[80:83], v[184:187], v[240:243], v[80:83]
	s_setprio 0
	s_setprio 1
	v_mfma_f32_16x16x32_bf16 v[124:127], v[188:191], v[204:207], v[124:127]
	v_mfma_f32_16x16x32_bf16 v[120:123], v[196:199], v[204:207], v[120:123]
	v_mfma_f32_16x16x32_bf16 v[108:111], v[188:191], v[212:215], v[108:111]
	v_mfma_f32_16x16x32_bf16 v[104:107], v[196:199], v[212:215], v[104:107]
	v_mfma_f32_16x16x32_bf16 v[92:95], v[188:191], v[220:223], v[92:95]
	v_mfma_f32_16x16x32_bf16 v[88:91], v[196:199], v[220:223], v[88:91]
	v_mfma_f32_16x16x32_bf16 v[76:79], v[188:191], v[236:239], v[76:79]
	v_mfma_f32_16x16x32_bf16 v[72:75], v[196:199], v[236:239], v[72:75]
	v_mfma_f32_16x16x32_bf16 v[124:127], v[192:195], v[208:211], v[124:127]
	v_mfma_f32_16x16x32_bf16 v[120:123], v[200:203], v[208:211], v[120:123]
	v_mfma_f32_16x16x32_bf16 v[108:111], v[192:195], v[216:219], v[108:111]
	v_mfma_f32_16x16x32_bf16 v[104:107], v[200:203], v[216:219], v[104:107]
	v_mfma_f32_16x16x32_bf16 v[92:95], v[192:195], v[224:227], v[92:95]
	v_mfma_f32_16x16x32_bf16 v[88:91], v[200:203], v[224:227], v[88:91]
	v_mfma_f32_16x16x32_bf16 v[76:79], v[192:195], v[240:243], v[76:79]
	v_mfma_f32_16x16x32_bf16 v[72:75], v[200:203], v[240:243], v[72:75]
	s_setprio 0
	s_barrier
	s_add_i32 s71, s53, s40
	s_mov_b32 m0, s71
	ds_read_b128 v[204:207], v166 offset:16384
	ds_read_b128 v[208:211], v166 offset:17408
	ds_read_b128 v[212:215], v166 offset:18432
	ds_read_b128 v[216:219], v166 offset:19456
	global_load_lds_dwordx4 v138, s[28:29]
	s_add_i32 m0, s71, 0x2000
	s_add_u32 s72, s28, 0x100000
	s_addc_u32 s73, s29, 0
	s_add_i32 s71, s54, s40
	global_load_lds_dwordx4 v142, s[28:29]
	s_mov_b32 m0, s71
	ds_read_b128 v[240:243], v166 offset:23552
	global_load_lds_dwordx4 v138, s[72:73]
	s_add_i32 m0, s71, 0x2000
	ds_read_b128 v[236:239], v166 offset:22528
	global_load_lds_dwordx4 v142, s[72:73]
	s_mov_b32 m0, s43
	ds_read_b128 v[224:227], v166 offset:21504
	global_load_lds_dwordx4 v136, s[30:31]
	s_mov_b32 m0, s44
	ds_read_b128 v[220:223], v166 offset:20480
	global_load_lds_dwordx4 v140, s[30:31]
	s_waitcnt vmcnt(10) lgkmcnt(0)
	s_barrier
	s_setprio 1
	v_mfma_f32_16x16x32_bf16 v[68:71], v[172:175], v[204:207], v[68:71]
	v_mfma_f32_16x16x32_bf16 v[64:67], v[180:183], v[204:207], v[64:67]
	v_mfma_f32_16x16x32_bf16 v[52:55], v[172:175], v[212:215], v[52:55]
	v_mfma_f32_16x16x32_bf16 v[48:51], v[180:183], v[212:215], v[48:51]
	v_mfma_f32_16x16x32_bf16 v[36:39], v[172:175], v[220:223], v[36:39]
	v_mfma_f32_16x16x32_bf16 v[32:35], v[180:183], v[220:223], v[32:35]
	v_mfma_f32_16x16x32_bf16 v[20:23], v[172:175], v[236:239], v[20:23]
	v_mfma_f32_16x16x32_bf16 v[16:19], v[180:183], v[236:239], v[16:19]
	v_mfma_f32_16x16x32_bf16 v[68:71], v[176:179], v[208:211], v[68:71]
	v_mfma_f32_16x16x32_bf16 v[64:67], v[184:187], v[208:211], v[64:67]
	v_mfma_f32_16x16x32_bf16 v[52:55], v[176:179], v[216:219], v[52:55]
	v_mfma_f32_16x16x32_bf16 v[48:51], v[184:187], v[216:219], v[48:51]
	v_mfma_f32_16x16x32_bf16 v[36:39], v[176:179], v[224:227], v[36:39]
	v_mfma_f32_16x16x32_bf16 v[32:35], v[184:187], v[224:227], v[32:35]
	v_mfma_f32_16x16x32_bf16 v[20:23], v[176:179], v[240:243], v[20:23]
	v_mfma_f32_16x16x32_bf16 v[16:19], v[184:187], v[240:243], v[16:19]
	s_setprio 0
	s_setprio 1
	v_mfma_f32_16x16x32_bf16 v[60:63], v[188:191], v[204:207], v[60:63]
	v_mfma_f32_16x16x32_bf16 v[56:59], v[196:199], v[204:207], v[56:59]
	v_mfma_f32_16x16x32_bf16 v[44:47], v[188:191], v[212:215], v[44:47]
	v_mfma_f32_16x16x32_bf16 v[40:43], v[196:199], v[212:215], v[40:43]
	v_mfma_f32_16x16x32_bf16 v[28:31], v[188:191], v[220:223], v[28:31]
	v_mfma_f32_16x16x32_bf16 v[24:27], v[196:199], v[220:223], v[24:27]
	v_mfma_f32_16x16x32_bf16 v[12:15], v[188:191], v[236:239], v[12:15]
	v_mfma_f32_16x16x32_bf16 v[6:9], v[196:199], v[236:239], v[8:11]
	v_mfma_f32_16x16x32_bf16 v[60:63], v[192:195], v[208:211], v[60:63]
	v_mfma_f32_16x16x32_bf16 v[56:59], v[200:203], v[208:211], v[56:59]
	v_mfma_f32_16x16x32_bf16 v[44:47], v[192:195], v[216:219], v[44:47]
	v_mfma_f32_16x16x32_bf16 v[40:43], v[200:203], v[216:219], v[40:43]
	v_mfma_f32_16x16x32_bf16 v[28:31], v[192:195], v[224:227], v[28:31]
	v_mfma_f32_16x16x32_bf16 v[24:27], v[200:203], v[224:227], v[24:27]
	v_mfma_f32_16x16x32_bf16 v[12:15], v[192:195], v[240:243], v[12:15]
	v_mfma_f32_16x16x32_bf16 v[6:9], v[200:203], v[240:243], v[6:9]
	s_setprio 0
	s_barrier
	s_add_i32 s71, 0, 0x18000
	s_add_i32 s72, 0, 0x1c000
	ds_read_b128 v[172:175], v163 offset:32768
	ds_read_b128 v[176:179], v163 offset:33792
	ds_read_b128 v[180:183], v163 offset:34816
	ds_read_b128 v[184:187], v163 offset:35840
	ds_read_b128 v[188:191], v163 offset:49152
	ds_read_b128 v[192:195], v163 offset:50176
	ds_read_b128 v[196:199], v163 offset:51200
	ds_read_b128 v[200:203], v163 offset:52224
	s_add_u32 s30, s30, 0x100000
	s_addc_u32 s31, s31, 0
	s_mov_b32 m0, s45
	ds_read_b128 v[204:207], v166 offset:32768
	ds_read_b128 v[208:211], v166 offset:33792
	ds_read_b128 v[212:215], v166 offset:34816
	ds_read_b128 v[216:219], v166 offset:35840
	ds_read_b128 v[220:223], v166 offset:36864
	ds_read_b128 v[224:227], v166 offset:37888
	ds_read_b128 v[236:239], v166 offset:38912
	global_load_lds_dwordx4 v136, s[30:31]
	s_mov_b32 m0, s46
	ds_read_b128 v[240:243], v166 offset:39936
	global_load_lds_dwordx4 v140, s[30:31]
	s_waitcnt vmcnt(8) lgkmcnt(0)
	s_barrier
	s_setprio 1
	v_mfma_f32_16x16x32_bf16 v[132:135], v[172:175], v[204:207], v[132:135]
	v_mfma_f32_16x16x32_bf16 v[128:131], v[180:183], v[204:207], v[128:131]
	v_mfma_f32_16x16x32_bf16 v[116:119], v[172:175], v[212:215], v[116:119]
	v_mfma_f32_16x16x32_bf16 v[112:115], v[180:183], v[212:215], v[112:115]
	v_mfma_f32_16x16x32_bf16 v[100:103], v[172:175], v[220:223], v[100:103]
	v_max3_f32 v0, v0, |v152|, |v168|
	v_mfma_f32_16x16x32_bf16 v[96:99], v[180:183], v[220:223], v[96:99]
	v_max3_f32 v1, v1, |v153|, |v169|
	v_mfma_f32_16x16x32_bf16 v[84:87], v[172:175], v[236:239], v[84:87]
	v_max3_f32 v2, v2, |v154|, |v170|
	v_mfma_f32_16x16x32_bf16 v[80:83], v[180:183], v[236:239], v[80:83]
	v_max3_f32 v3, v3, |v155|, |v171|
	v_mfma_f32_16x16x32_bf16 v[132:135], v[176:179], v[208:211], v[132:135]
	v_mfma_f32_16x16x32_bf16 v[128:131], v[184:187], v[208:211], v[128:131]
	v_mfma_f32_16x16x32_bf16 v[116:119], v[176:179], v[216:219], v[116:119]
	v_mfma_f32_16x16x32_bf16 v[112:115], v[184:187], v[216:219], v[112:115]
	v_mfma_f32_16x16x32_bf16 v[100:103], v[176:179], v[224:227], v[100:103]
	v_mfma_f32_16x16x32_bf16 v[96:99], v[184:187], v[224:227], v[96:99]
	v_mfma_f32_16x16x32_bf16 v[84:87], v[176:179], v[240:243], v[84:87]
	v_mfma_f32_16x16x32_bf16 v[80:83], v[184:187], v[240:243], v[80:83]
	s_setprio 0
	s_setprio 1
	v_mfma_f32_16x16x32_bf16 v[124:127], v[188:191], v[204:207], v[124:127]
	v_mfma_f32_16x16x32_bf16 v[120:123], v[196:199], v[204:207], v[120:123]
	v_mfma_f32_16x16x32_bf16 v[108:111], v[188:191], v[212:215], v[108:111]
	v_mfma_f32_16x16x32_bf16 v[104:107], v[196:199], v[212:215], v[104:107]
	v_mfma_f32_16x16x32_bf16 v[92:95], v[188:191], v[220:223], v[92:95]
	v_mfma_f32_16x16x32_bf16 v[88:91], v[196:199], v[220:223], v[88:91]
	v_mfma_f32_16x16x32_bf16 v[76:79], v[188:191], v[236:239], v[76:79]
	v_mfma_f32_16x16x32_bf16 v[72:75], v[196:199], v[236:239], v[72:75]
	v_mfma_f32_16x16x32_bf16 v[124:127], v[192:195], v[208:211], v[124:127]
	v_mfma_f32_16x16x32_bf16 v[120:123], v[200:203], v[208:211], v[120:123]
	v_mfma_f32_16x16x32_bf16 v[108:111], v[192:195], v[216:219], v[108:111]
	v_mfma_f32_16x16x32_bf16 v[104:107], v[200:203], v[216:219], v[104:107]
	v_mfma_f32_16x16x32_bf16 v[92:95], v[192:195], v[224:227], v[92:95]
	v_mfma_f32_16x16x32_bf16 v[88:91], v[200:203], v[224:227], v[88:91]
	v_mfma_f32_16x16x32_bf16 v[76:79], v[192:195], v[240:243], v[76:79]
	v_mfma_f32_16x16x32_bf16 v[72:75], v[200:203], v[240:243], v[72:75]
	s_setprio 0
	s_barrier
	s_add_u32 s74, s28, s6
	s_addc_u32 s75, s29, s7
	s_add_u32 s76, s30, s6
	s_addc_u32 s77, s31, s7
	s_sub_u32 s76, s76, 0x100000
	s_subb_u32 s77, s77, 0
	s_add_i32 s30, s71, s40
	s_mov_b32 m0, s30
	ds_read_b128 v[152:155], v166 offset:49152
	ds_read_b128 v[168:171], v166 offset:50176
	ds_read_b128 v[204:207], v166 offset:51200
	ds_read_b128 v[208:211], v166 offset:52224
	global_load_lds_dwordx4 v138, s[74:75]
	s_add_i32 m0, s30, 0x2000
	s_add_u32 s28, s28, 0x100080
	s_addc_u32 s29, s29, 0
	s_add_i32 s30, s72, s40
	global_load_lds_dwordx4 v142, s[74:75]
	s_mov_b32 m0, s30
	ds_read_b128 v[224:227], v166 offset:56320
	global_load_lds_dwordx4 v138, s[28:29]
	s_add_i32 m0, s30, 0x2000
	ds_read_b128 v[220:223], v166 offset:55296
	global_load_lds_dwordx4 v142, s[28:29]
	s_mov_b32 m0, s49
	ds_read_b128 v[216:219], v166 offset:54272
	global_load_lds_dwordx4 v136, s[76:77]
	s_mov_b32 m0, s50
	ds_read_b128 v[212:215], v166 offset:53248
	global_load_lds_dwordx4 v140, s[76:77]
	s_waitcnt vmcnt(8) lgkmcnt(0)
	s_barrier
	s_setprio 1
	v_mfma_f32_16x16x32_bf16 v[68:71], v[172:175], v[152:155], v[68:71]
	v_mfma_f32_16x16x32_bf16 v[64:67], v[180:183], v[152:155], v[64:67]
	v_mfma_f32_16x16x32_bf16 v[52:55], v[172:175], v[204:207], v[52:55]
	v_mfma_f32_16x16x32_bf16 v[48:51], v[180:183], v[204:207], v[48:51]
	v_mfma_f32_16x16x32_bf16 v[36:39], v[172:175], v[212:215], v[36:39]
	v_mfma_f32_16x16x32_bf16 v[32:35], v[180:183], v[212:215], v[32:35]
	v_mfma_f32_16x16x32_bf16 v[20:23], v[172:175], v[220:223], v[20:23]
	v_mfma_f32_16x16x32_bf16 v[16:19], v[180:183], v[220:223], v[16:19]
	v_mfma_f32_16x16x32_bf16 v[68:71], v[176:179], v[168:171], v[68:71]
	v_mfma_f32_16x16x32_bf16 v[64:67], v[184:187], v[168:171], v[64:67]
	v_mfma_f32_16x16x32_bf16 v[52:55], v[176:179], v[208:211], v[52:55]
	v_mfma_f32_16x16x32_bf16 v[48:51], v[184:187], v[208:211], v[48:51]
	v_mfma_f32_16x16x32_bf16 v[36:39], v[176:179], v[216:219], v[36:39]
	v_mfma_f32_16x16x32_bf16 v[32:35], v[184:187], v[216:219], v[32:35]
	v_mfma_f32_16x16x32_bf16 v[20:23], v[176:179], v[224:227], v[20:23]
	v_mfma_f32_16x16x32_bf16 v[16:19], v[184:187], v[224:227], v[16:19]
	s_setprio 0
	s_setprio 1
	v_mfma_f32_16x16x32_bf16 v[60:63], v[188:191], v[152:155], v[60:63]
	v_mfma_f32_16x16x32_bf16 v[56:59], v[196:199], v[152:155], v[56:59]
	v_mfma_f32_16x16x32_bf16 v[44:47], v[188:191], v[204:207], v[44:47]
	v_mfma_f32_16x16x32_bf16 v[40:43], v[196:199], v[204:207], v[40:43]
	v_mfma_f32_16x16x32_bf16 v[28:31], v[188:191], v[212:215], v[28:31]
	v_mfma_f32_16x16x32_bf16 v[24:27], v[196:199], v[212:215], v[24:27]
	v_mfma_f32_16x16x32_bf16 v[10:13], v[188:191], v[220:223], v[12:15]
	v_mfma_f32_16x16x32_bf16 v[6:9], v[196:199], v[220:223], v[6:9]
	v_mfma_f32_16x16x32_bf16 v[60:63], v[192:195], v[168:171], v[60:63]
	v_mfma_f32_16x16x32_bf16 v[56:59], v[200:203], v[168:171], v[56:59]
	v_mfma_f32_16x16x32_bf16 v[44:47], v[192:195], v[208:211], v[44:47]
	v_mfma_f32_16x16x32_bf16 v[40:43], v[200:203], v[208:211], v[40:43]
	v_mfma_f32_16x16x32_bf16 v[28:31], v[192:195], v[216:219], v[28:31]
	v_mfma_f32_16x16x32_bf16 v[24:27], v[200:203], v[216:219], v[24:27]
	v_mfma_f32_16x16x32_bf16 v[12:15], v[192:195], v[224:227], v[10:13]
	v_mfma_f32_16x16x32_bf16 v[8:11], v[200:203], v[224:227], v[6:9]
	s_setprio 0
	s_barrier
	s_add_u32 s26, s26, 0x100
	s_addc_u32 s27, s27, 0
	s_add_u32 s69, s69, 0x100
	s_addc_u32 s70, s70, 0
	s_cmp_ge_i32 s8, s63
	s_cbranch_scc0 .LBB0_1018

.LBB0_1238:
	s_add_i32 s74, s38, 2
	s_add_u32 s39, s36, 0xfff80080
	s_addc_u32 s40, s37, -1
	s_cmp_eq_u32 s71, s38
	s_cselect_b32 s41, s67, s40
	s_cselect_b32 s40, s68, s39
	ds_read_b128 v[140:143], v177
	ds_read_b128 v[144:147], v177 offset:1024
	ds_read_b128 v[148:151], v177 offset:2048
	ds_read_b128 v[152:155], v177 offset:3072
	ds_read_b128 v[156:159], v177 offset:16384
	ds_read_b128 v[160:163], v177 offset:17408
	ds_read_b128 v[164:167], v177 offset:18432
	ds_read_b128 v[168:171], v177 offset:19456
	s_cselect_b32 s38, s70, s72
	s_cselect_b32 s39, s69, s73
	s_add_i32 m0, s45, 0xc000
	ds_read_b128 v[180:183], v178
	ds_read_b128 v[184:187], v178 offset:1024
	ds_read_b128 v[188:191], v178 offset:2048
	ds_read_b128 v[192:195], v178 offset:3072
	ds_read_b128 v[196:199], v178 offset:4096
	ds_read_b128 v[200:203], v178 offset:5120
	ds_read_b128 v[204:207], v178 offset:6144
	global_load_lds_dwordx4 v136, s[36:37]
	s_add_i32 m0, s45, 0xe000
	ds_read_b128 v[208:211], v178 offset:7168
	global_load_lds_dwordx4 v138, s[36:37]
	s_waitcnt vmcnt(8) lgkmcnt(0)
	s_barrier
	s_setprio 1
	v_mfma_i32_16x16x64_i8 v[124:127], v[140:143], v[180:183], v[124:127]
	v_mfma_i32_16x16x64_i8 v[120:123], v[148:151], v[180:183], v[120:123]
	v_mfma_i32_16x16x64_i8 v[116:119], v[140:143], v[188:191], v[116:119]
	v_mfma_i32_16x16x64_i8 v[112:115], v[148:151], v[188:191], v[112:115]
	v_mfma_i32_16x16x64_i8 v[104:107], v[140:143], v[196:199], v[104:107]
	v_mfma_i32_16x16x64_i8 v[96:99], v[148:151], v[196:199], v[96:99]
	v_mfma_i32_16x16x64_i8 v[88:91], v[140:143], v[204:207], v[88:91]
	v_mfma_i32_16x16x64_i8 v[80:83], v[148:151], v[204:207], v[80:83]
	v_mfma_i32_16x16x64_i8 v[124:127], v[144:147], v[184:187], v[124:127]
	v_mfma_i32_16x16x64_i8 v[120:123], v[152:155], v[184:187], v[120:123]
	v_mfma_i32_16x16x64_i8 v[116:119], v[144:147], v[192:195], v[116:119]
	v_mfma_i32_16x16x64_i8 v[112:115], v[152:155], v[192:195], v[112:115]
	v_mfma_i32_16x16x64_i8 v[104:107], v[144:147], v[200:203], v[104:107]
	v_mfma_i32_16x16x64_i8 v[96:99], v[152:155], v[200:203], v[96:99]
	v_mfma_i32_16x16x64_i8 v[88:91], v[144:147], v[208:211], v[88:91]
	v_mfma_i32_16x16x64_i8 v[80:83], v[152:155], v[208:211], v[80:83]
	s_setprio 0
	s_setprio 1
	v_mfma_i32_16x16x64_i8 v[108:111], v[156:159], v[180:183], v[108:111]
	v_mfma_i32_16x16x64_i8 v[100:103], v[164:167], v[180:183], v[100:103]
	v_mfma_i32_16x16x64_i8 v[92:95], v[156:159], v[188:191], v[92:95]
	v_mfma_i32_16x16x64_i8 v[84:87], v[164:167], v[188:191], v[84:87]
	v_mfma_i32_16x16x64_i8 v[76:79], v[156:159], v[196:199], v[76:79]
	v_mfma_i32_16x16x64_i8 v[72:75], v[164:167], v[196:199], v[72:75]
	v_mfma_i32_16x16x64_i8 v[68:71], v[156:159], v[204:207], v[68:71]
	v_mfma_i32_16x16x64_i8 v[64:67], v[164:167], v[204:207], v[64:67]
	v_mfma_i32_16x16x64_i8 v[108:111], v[160:163], v[184:187], v[108:111]
	v_mfma_i32_16x16x64_i8 v[100:103], v[168:171], v[184:187], v[100:103]
	v_mfma_i32_16x16x64_i8 v[92:95], v[160:163], v[192:195], v[92:95]
	v_mfma_i32_16x16x64_i8 v[84:87], v[168:171], v[192:195], v[84:87]
	v_mfma_i32_16x16x64_i8 v[76:79], v[160:163], v[200:203], v[76:79]
	v_mfma_i32_16x16x64_i8 v[72:75], v[168:171], v[200:203], v[72:75]
	v_mfma_i32_16x16x64_i8 v[68:71], v[160:163], v[208:211], v[68:71]
	v_mfma_i32_16x16x64_i8 v[64:67], v[168:171], v[208:211], v[64:67]
	s_setprio 0
	s_barrier
	s_add_i32 s75, s55, s42
	s_mov_b32 m0, s75
	ds_read_b128 v[180:183], v178 offset:16384
	ds_read_b128 v[184:187], v178 offset:17408
	ds_read_b128 v[188:191], v178 offset:18432
	ds_read_b128 v[192:195], v178 offset:19456
	global_load_lds_dwordx4 v130, s[38:39]
	s_add_i32 m0, s75, 0x2000
	s_add_u32 s76, s38, 0x80000
	s_addc_u32 s77, s39, 0
	s_add_i32 s75, s60, s42
	global_load_lds_dwordx4 v134, s[38:39]
	s_mov_b32 m0, s75
	ds_read_b128 v[208:211], v178 offset:23552
	global_load_lds_dwordx4 v130, s[76:77]
	s_add_i32 m0, s75, 0x2000
	ds_read_b128 v[204:207], v178 offset:22528
	global_load_lds_dwordx4 v134, s[76:77]
	s_mov_b32 m0, s45
	ds_read_b128 v[200:203], v178 offset:21504
	global_load_lds_dwordx4 v128, s[40:41]
	s_mov_b32 m0, s46
	ds_read_b128 v[196:199], v178 offset:20480
	global_load_lds_dwordx4 v132, s[40:41]
	s_waitcnt vmcnt(8) lgkmcnt(0)
	s_barrier
	s_setprio 1
	v_mfma_i32_16x16x64_i8 v[60:63], v[140:143], v[180:183], v[60:63]
	v_mfma_i32_16x16x64_i8 v[56:59], v[148:151], v[180:183], v[56:59]
	v_mfma_i32_16x16x64_i8 v[52:55], v[140:143], v[188:191], v[52:55]
	v_mfma_i32_16x16x64_i8 v[48:51], v[148:151], v[188:191], v[48:51]
	v_mfma_i32_16x16x64_i8 v[40:43], v[140:143], v[196:199], v[40:43]
	v_mfma_i32_16x16x64_i8 v[32:35], v[148:151], v[196:199], v[32:35]
	v_mfma_i32_16x16x64_i8 v[24:27], v[140:143], v[204:207], v[24:27]
	v_mfma_i32_16x16x64_i8 v[16:19], v[148:151], v[204:207], v[16:19]
	v_mfma_i32_16x16x64_i8 v[60:63], v[144:147], v[184:187], v[60:63]
	v_mfma_i32_16x16x64_i8 v[56:59], v[152:155], v[184:187], v[56:59]
	v_mfma_i32_16x16x64_i8 v[52:55], v[144:147], v[192:195], v[52:55]
	v_mfma_i32_16x16x64_i8 v[48:51], v[152:155], v[192:195], v[48:51]
	v_mfma_i32_16x16x64_i8 v[40:43], v[144:147], v[200:203], v[40:43]
	v_mfma_i32_16x16x64_i8 v[32:35], v[152:155], v[200:203], v[32:35]
	v_mfma_i32_16x16x64_i8 v[24:27], v[144:147], v[208:211], v[24:27]
	v_mfma_i32_16x16x64_i8 v[16:19], v[152:155], v[208:211], v[16:19]
	s_setprio 0
	s_setprio 1
	v_mfma_i32_16x16x64_i8 v[44:47], v[156:159], v[180:183], v[44:47]
	v_mfma_i32_16x16x64_i8 v[36:39], v[164:167], v[180:183], v[36:39]
	v_mfma_i32_16x16x64_i8 v[28:31], v[156:159], v[188:191], v[28:31]
	v_mfma_i32_16x16x64_i8 v[20:23], v[164:167], v[188:191], v[20:23]
	v_mfma_i32_16x16x64_i8 v[12:15], v[156:159], v[196:199], v[12:15]
	v_mfma_i32_16x16x64_i8 v[8:11], v[164:167], v[196:199], v[8:11]
	v_mfma_i32_16x16x64_i8 v[4:7], v[156:159], v[204:207], v[4:7]
	v_mfma_i32_16x16x64_i8 v[0:3], v[164:167], v[204:207], v[0:3]
	v_mfma_i32_16x16x64_i8 v[44:47], v[160:163], v[184:187], v[44:47]
	v_mfma_i32_16x16x64_i8 v[36:39], v[168:171], v[184:187], v[36:39]
	v_mfma_i32_16x16x64_i8 v[28:31], v[160:163], v[192:195], v[28:31]
	v_mfma_i32_16x16x64_i8 v[20:23], v[168:171], v[192:195], v[20:23]
	v_mfma_i32_16x16x64_i8 v[12:15], v[160:163], v[200:203], v[12:15]
	v_mfma_i32_16x16x64_i8 v[8:11], v[168:171], v[200:203], v[8:11]
	v_mfma_i32_16x16x64_i8 v[4:7], v[160:163], v[208:211], v[4:7]
	v_mfma_i32_16x16x64_i8 v[0:3], v[168:171], v[208:211], v[0:3]
	s_setprio 0
	s_barrier
	s_add_i32 s75, 0, 0x18000
	s_add_i32 s76, 0, 0x1c000
	ds_read_b128 v[140:143], v177 offset:32768
	ds_read_b128 v[144:147], v177 offset:33792
	ds_read_b128 v[148:151], v177 offset:34816
	ds_read_b128 v[152:155], v177 offset:35840
	ds_read_b128 v[156:159], v177 offset:49152
	ds_read_b128 v[160:163], v177 offset:50176
	ds_read_b128 v[164:167], v177 offset:51200
	ds_read_b128 v[168:171], v177 offset:52224
	s_add_u32 s40, s40, 0x80000
	s_addc_u32 s41, s41, 0
	s_mov_b32 m0, s47
	ds_read_b128 v[180:183], v178 offset:32768
	ds_read_b128 v[184:187], v178 offset:33792
	ds_read_b128 v[188:191], v178 offset:34816
	ds_read_b128 v[192:195], v178 offset:35840
	ds_read_b128 v[196:199], v178 offset:36864
	ds_read_b128 v[200:203], v178 offset:37888
	ds_read_b128 v[204:207], v178 offset:38912
	global_load_lds_dwordx4 v128, s[40:41]
	s_mov_b32 m0, s48
	ds_read_b128 v[208:211], v178 offset:39936
	global_load_lds_dwordx4 v132, s[40:41]
	s_waitcnt vmcnt(8) lgkmcnt(0)
	s_barrier
	s_setprio 1
	v_mfma_i32_16x16x64_i8 v[124:127], v[140:143], v[180:183], v[124:127]
	v_mfma_i32_16x16x64_i8 v[120:123], v[148:151], v[180:183], v[120:123]
	v_mfma_i32_16x16x64_i8 v[116:119], v[140:143], v[188:191], v[116:119]
	v_mfma_i32_16x16x64_i8 v[112:115], v[148:151], v[188:191], v[112:115]
	v_mfma_i32_16x16x64_i8 v[104:107], v[140:143], v[196:199], v[104:107]
	v_mfma_i32_16x16x64_i8 v[96:99], v[148:151], v[196:199], v[96:99]
	v_mfma_i32_16x16x64_i8 v[88:91], v[140:143], v[204:207], v[88:91]
	v_mfma_i32_16x16x64_i8 v[80:83], v[148:151], v[204:207], v[80:83]
	v_mfma_i32_16x16x64_i8 v[124:127], v[144:147], v[184:187], v[124:127]
	v_mfma_i32_16x16x64_i8 v[120:123], v[152:155], v[184:187], v[120:123]
	v_mfma_i32_16x16x64_i8 v[116:119], v[144:147], v[192:195], v[116:119]
	v_mfma_i32_16x16x64_i8 v[112:115], v[152:155], v[192:195], v[112:115]
	v_mfma_i32_16x16x64_i8 v[104:107], v[144:147], v[200:203], v[104:107]
	v_mfma_i32_16x16x64_i8 v[96:99], v[152:155], v[200:203], v[96:99]
	v_mfma_i32_16x16x64_i8 v[88:91], v[144:147], v[208:211], v[88:91]
	v_mfma_i32_16x16x64_i8 v[80:83], v[152:155], v[208:211], v[80:83]
	s_setprio 0
	s_setprio 1
	v_mfma_i32_16x16x64_i8 v[108:111], v[156:159], v[180:183], v[108:111]
	v_mfma_i32_16x16x64_i8 v[100:103], v[164:167], v[180:183], v[100:103]
	v_mfma_i32_16x16x64_i8 v[92:95], v[156:159], v[188:191], v[92:95]
	v_mfma_i32_16x16x64_i8 v[84:87], v[164:167], v[188:191], v[84:87]
	v_mfma_i32_16x16x64_i8 v[76:79], v[156:159], v[196:199], v[76:79]
	v_mfma_i32_16x16x64_i8 v[72:75], v[164:167], v[196:199], v[72:75]
	v_mfma_i32_16x16x64_i8 v[68:71], v[156:159], v[204:207], v[68:71]
	v_mfma_i32_16x16x64_i8 v[64:67], v[164:167], v[204:207], v[64:67]
	v_mfma_i32_16x16x64_i8 v[108:111], v[160:163], v[184:187], v[108:111]
	v_mfma_i32_16x16x64_i8 v[100:103], v[168:171], v[184:187], v[100:103]
	v_mfma_i32_16x16x64_i8 v[92:95], v[160:163], v[192:195], v[92:95]
	v_mfma_i32_16x16x64_i8 v[84:87], v[168:171], v[192:195], v[84:87]
	v_mfma_i32_16x16x64_i8 v[76:79], v[160:163], v[200:203], v[76:79]
	v_mfma_i32_16x16x64_i8 v[72:75], v[168:171], v[200:203], v[72:75]
	v_mfma_i32_16x16x64_i8 v[68:71], v[160:163], v[208:211], v[68:71]
	v_mfma_i32_16x16x64_i8 v[64:67], v[168:171], v[208:211], v[64:67]
	s_setprio 0
	s_barrier
	s_add_u32 s98, s38, s20
	s_addc_u32 s99, s39, s21
	s_add_u32 s100, s40, s20
	s_addc_u32 s101, s41, s21
	s_sub_u32 s100, s100, 0x80000
	s_subb_u32 s101, s101, 0
	s_add_i32 s40, s75, s42
	s_mov_b32 m0, s40
	ds_read_b128 v[180:183], v178 offset:49152
	ds_read_b128 v[184:187], v178 offset:50176
	ds_read_b128 v[188:191], v178 offset:51200
	ds_read_b128 v[192:195], v178 offset:52224
	global_load_lds_dwordx4 v130, s[98:99]
	s_add_i32 m0, s40, 0x2000
	s_add_u32 s38, s38, 0x80080
	s_addc_u32 s39, s39, 0
	s_add_i32 s40, s76, s42
	global_load_lds_dwordx4 v134, s[98:99]
	s_mov_b32 m0, s40
	ds_read_b128 v[208:211], v178 offset:56320
	global_load_lds_dwordx4 v130, s[38:39]
	s_add_i32 m0, s40, 0x2000
	ds_read_b128 v[204:207], v178 offset:55296
	global_load_lds_dwordx4 v134, s[38:39]
	s_mov_b32 m0, s51
	ds_read_b128 v[200:203], v178 offset:54272
	global_load_lds_dwordx4 v128, s[100:101]
	s_mov_b32 m0, s52
	ds_read_b128 v[196:199], v178 offset:53248
	global_load_lds_dwordx4 v132, s[100:101]
	s_waitcnt vmcnt(8) lgkmcnt(0)
	s_barrier
	s_setprio 1
	v_mfma_i32_16x16x64_i8 v[60:63], v[140:143], v[180:183], v[60:63]
	v_mfma_i32_16x16x64_i8 v[56:59], v[148:151], v[180:183], v[56:59]
	v_mfma_i32_16x16x64_i8 v[52:55], v[140:143], v[188:191], v[52:55]
	v_mfma_i32_16x16x64_i8 v[48:51], v[148:151], v[188:191], v[48:51]
	v_mfma_i32_16x16x64_i8 v[40:43], v[140:143], v[196:199], v[40:43]
	v_mfma_i32_16x16x64_i8 v[32:35], v[148:151], v[196:199], v[32:35]
	v_mfma_i32_16x16x64_i8 v[24:27], v[140:143], v[204:207], v[24:27]
	v_mfma_i32_16x16x64_i8 v[16:19], v[148:151], v[204:207], v[16:19]
	v_mfma_i32_16x16x64_i8 v[60:63], v[144:147], v[184:187], v[60:63]
	v_mfma_i32_16x16x64_i8 v[56:59], v[152:155], v[184:187], v[56:59]
	v_mfma_i32_16x16x64_i8 v[52:55], v[144:147], v[192:195], v[52:55]
	v_mfma_i32_16x16x64_i8 v[48:51], v[152:155], v[192:195], v[48:51]
	v_mfma_i32_16x16x64_i8 v[40:43], v[144:147], v[200:203], v[40:43]
	v_mfma_i32_16x16x64_i8 v[32:35], v[152:155], v[200:203], v[32:35]
	v_mfma_i32_16x16x64_i8 v[24:27], v[144:147], v[208:211], v[24:27]
	v_mfma_i32_16x16x64_i8 v[16:19], v[152:155], v[208:211], v[16:19]
	s_setprio 0
	s_setprio 1
	v_mfma_i32_16x16x64_i8 v[44:47], v[156:159], v[180:183], v[44:47]
	v_mfma_i32_16x16x64_i8 v[36:39], v[164:167], v[180:183], v[36:39]
	v_mfma_i32_16x16x64_i8 v[28:31], v[156:159], v[188:191], v[28:31]
	v_mfma_i32_16x16x64_i8 v[20:23], v[164:167], v[188:191], v[20:23]
	v_mfma_i32_16x16x64_i8 v[12:15], v[156:159], v[196:199], v[12:15]
	v_mfma_i32_16x16x64_i8 v[8:11], v[164:167], v[196:199], v[8:11]
	v_mfma_i32_16x16x64_i8 v[4:7], v[156:159], v[204:207], v[4:7]
	v_mfma_i32_16x16x64_i8 v[0:3], v[164:167], v[204:207], v[0:3]
	v_mfma_i32_16x16x64_i8 v[44:47], v[160:163], v[184:187], v[44:47]
	v_mfma_i32_16x16x64_i8 v[36:39], v[168:171], v[184:187], v[36:39]
	v_mfma_i32_16x16x64_i8 v[28:31], v[160:163], v[192:195], v[28:31]
	v_mfma_i32_16x16x64_i8 v[20:23], v[168:171], v[192:195], v[20:23]
	v_mfma_i32_16x16x64_i8 v[12:15], v[160:163], v[200:203], v[12:15]
	v_mfma_i32_16x16x64_i8 v[8:11], v[168:171], v[200:203], v[8:11]
	v_mfma_i32_16x16x64_i8 v[4:7], v[160:163], v[208:211], v[4:7]
	v_mfma_i32_16x16x64_i8 v[0:3], v[168:171], v[208:211], v[0:3]
	s_setprio 0
	s_barrier
	s_add_u32 s36, s36, 0x100
	s_addc_u32 s37, s37, 0
	s_add_u32 s72, s72, 0x100
	s_addc_u32 s73, s73, 0
	s_cmp_ge_i32 s74, s8
	s_mov_b32 s38, s74
	s_cbranch_scc0 .LBB0_1238

.Lq_body_L:
	s_add_i32 s74, s38, 2
	s_add_u32 s39, s36, 0xfff80080
	s_addc_u32 s40, s37, -1
	s_cmp_eq_u32 s71, s38
	s_cselect_b32 s41, s67, s40
	s_cselect_b32 s40, s68, s39
	ds_read_b128 v[140:143], v177
	ds_read_b128 v[144:147], v177 offset:1024
	ds_read_b128 v[148:151], v177 offset:2048
	ds_read_b128 v[152:155], v177 offset:3072
	ds_read_b128 v[156:159], v177 offset:16384
	ds_read_b128 v[160:163], v177 offset:17408
	ds_read_b128 v[164:167], v177 offset:18432
	ds_read_b128 v[168:171], v177 offset:19456
	s_cselect_b32 s38, s70, s72
	s_cselect_b32 s39, s69, s73
	s_add_i32 m0, s45, 0xc000
	ds_read_b128 v[180:183], v178
	ds_read_b128 v[184:187], v178 offset:1024
	ds_read_b128 v[188:191], v178 offset:2048
	ds_read_b128 v[192:195], v178 offset:3072
	ds_read_b128 v[196:199], v178 offset:4096
	ds_read_b128 v[200:203], v178 offset:5120
	ds_read_b128 v[204:207], v178 offset:6144
	global_load_lds_dwordx4 v136, s[36:37]
	s_add_i32 m0, s45, 0xe000
	ds_read_b128 v[208:211], v178 offset:7168
	global_load_lds_dwordx4 v138, s[36:37]
	global_load_dwordx4 v[226:229], v223, s[100:101] nt
	s_add_u32 s84, s84, 1
	s_waitcnt vmcnt(9) lgkmcnt(0)
	s_barrier
	s_setprio 1
	v_mfma_i32_16x16x64_i8 v[124:127], v[140:143], v[180:183], v[124:127]
	v_mfma_i32_16x16x64_i8 v[120:123], v[148:151], v[180:183], v[120:123]
	v_mfma_i32_16x16x64_i8 v[116:119], v[140:143], v[188:191], v[116:119]
	v_mfma_i32_16x16x64_i8 v[112:115], v[148:151], v[188:191], v[112:115]
	v_mfma_i32_16x16x64_i8 v[104:107], v[140:143], v[196:199], v[104:107]
	v_mfma_i32_16x16x64_i8 v[96:99], v[148:151], v[196:199], v[96:99]
	v_mfma_i32_16x16x64_i8 v[88:91], v[140:143], v[204:207], v[88:91]
	v_mfma_i32_16x16x64_i8 v[80:83], v[148:151], v[204:207], v[80:83]
	v_mfma_i32_16x16x64_i8 v[124:127], v[144:147], v[184:187], v[124:127]
	v_mfma_i32_16x16x64_i8 v[120:123], v[152:155], v[184:187], v[120:123]
	v_mfma_i32_16x16x64_i8 v[116:119], v[144:147], v[192:195], v[116:119]
	v_mfma_i32_16x16x64_i8 v[112:115], v[152:155], v[192:195], v[112:115]
	v_mfma_i32_16x16x64_i8 v[104:107], v[144:147], v[200:203], v[104:107]
	v_mfma_i32_16x16x64_i8 v[96:99], v[152:155], v[200:203], v[96:99]
	v_mfma_i32_16x16x64_i8 v[88:91], v[144:147], v[208:211], v[88:91]
	v_mfma_i32_16x16x64_i8 v[80:83], v[152:155], v[208:211], v[80:83]
	s_setprio 0
	s_setprio 1
	v_mfma_i32_16x16x64_i8 v[108:111], v[156:159], v[180:183], v[108:111]
	v_mfma_i32_16x16x64_i8 v[100:103], v[164:167], v[180:183], v[100:103]
	v_mfma_i32_16x16x64_i8 v[92:95], v[156:159], v[188:191], v[92:95]
	v_mfma_i32_16x16x64_i8 v[84:87], v[164:167], v[188:191], v[84:87]
	v_mfma_i32_16x16x64_i8 v[76:79], v[156:159], v[196:199], v[76:79]
	v_mfma_i32_16x16x64_i8 v[72:75], v[164:167], v[196:199], v[72:75]
	v_mfma_i32_16x16x64_i8 v[68:71], v[156:159], v[204:207], v[68:71]
	v_mfma_i32_16x16x64_i8 v[64:67], v[164:167], v[204:207], v[64:67]
	v_mfma_i32_16x16x64_i8 v[108:111], v[160:163], v[184:187], v[108:111]
	v_mfma_i32_16x16x64_i8 v[100:103], v[168:171], v[184:187], v[100:103]
	v_mfma_i32_16x16x64_i8 v[92:95], v[160:163], v[192:195], v[92:95]
	v_mfma_i32_16x16x64_i8 v[84:87], v[168:171], v[192:195], v[84:87]
	v_mfma_i32_16x16x64_i8 v[76:79], v[160:163], v[200:203], v[76:79]
	v_mfma_i32_16x16x64_i8 v[72:75], v[168:171], v[200:203], v[72:75]
	v_mfma_i32_16x16x64_i8 v[68:71], v[160:163], v[208:211], v[68:71]
	v_mfma_i32_16x16x64_i8 v[64:67], v[168:171], v[208:211], v[64:67]
	s_setprio 0
	s_barrier
	s_add_i32 s75, s55, s42
	v_lshl_add_u64 v[172:173], s[38:39], 0, v[130:131]
	s_mov_b32 m0, s75
	ds_read_b128 v[180:183], v178 offset:16384
	ds_read_b128 v[184:187], v178 offset:17408
	ds_read_b128 v[188:191], v178 offset:18432
	ds_read_b128 v[192:195], v178 offset:19456
	ds_read_b128 v[196:199], v178 offset:20480
	global_load_lds_dwordx4 v130, s[38:39]
	s_add_i32 m0, s75, 0x2000
	s_add_u32 s76, s38, 0x80000
	v_lshl_add_u64 v[212:213], s[38:39], 0, v[134:135]
	s_addc_u32 s77, s39, 0
	s_add_i32 s75, s60, s42
	global_load_lds_dwordx4 v134, s[38:39]
	s_mov_b32 m0, s75
	v_lshl_add_u64 v[216:217], s[40:41], 0, v[132:133]
	global_load_lds_dwordx4 v130, s[76:77]
	s_add_i32 m0, s75, 0x2000
	ds_read_b128 v[208:211], v178 offset:23552
	global_load_lds_dwordx4 v134, s[76:77]
	v_lshl_add_u64 v[214:215], s[40:41], 0, v[128:129]
	s_mov_b32 m0, s45
	ds_read_b128 v[204:207], v178 offset:22528
	global_load_lds_dwordx4 v128, s[40:41]
	s_mov_b32 m0, s46
	ds_read_b128 v[200:203], v178 offset:21504
	global_load_lds_dwordx4 v132, s[40:41]
	s_waitcnt vmcnt(9) lgkmcnt(0)
	s_barrier
	s_setprio 1
	v_mfma_i32_16x16x64_i8 v[60:63], v[140:143], v[180:183], v[60:63]
	v_mfma_i32_16x16x64_i8 v[56:59], v[148:151], v[180:183], v[56:59]
	v_mfma_i32_16x16x64_i8 v[52:55], v[140:143], v[188:191], v[52:55]
	v_mfma_i32_16x16x64_i8 v[48:51], v[148:151], v[188:191], v[48:51]
	v_mfma_i32_16x16x64_i8 v[40:43], v[140:143], v[196:199], v[40:43]
	v_mfma_i32_16x16x64_i8 v[32:35], v[148:151], v[196:199], v[32:35]
	v_mfma_i32_16x16x64_i8 v[24:27], v[140:143], v[204:207], v[24:27]
	v_mfma_i32_16x16x64_i8 v[16:19], v[148:151], v[204:207], v[16:19]
	v_mfma_i32_16x16x64_i8 v[60:63], v[144:147], v[184:187], v[60:63]
	v_mfma_i32_16x16x64_i8 v[56:59], v[152:155], v[184:187], v[56:59]
	v_mfma_i32_16x16x64_i8 v[52:55], v[144:147], v[192:195], v[52:55]
	v_mfma_i32_16x16x64_i8 v[48:51], v[152:155], v[192:195], v[48:51]
	v_mfma_i32_16x16x64_i8 v[40:43], v[144:147], v[200:203], v[40:43]
	v_mfma_i32_16x16x64_i8 v[32:35], v[152:155], v[200:203], v[32:35]
	v_mfma_i32_16x16x64_i8 v[24:27], v[144:147], v[208:211], v[24:27]
	v_mfma_i32_16x16x64_i8 v[16:19], v[152:155], v[208:211], v[16:19]
	s_setprio 0
	s_setprio 1
	v_mfma_i32_16x16x64_i8 v[44:47], v[156:159], v[180:183], v[44:47]
	v_mfma_i32_16x16x64_i8 v[36:39], v[164:167], v[180:183], v[36:39]
	v_mfma_i32_16x16x64_i8 v[28:31], v[156:159], v[188:191], v[28:31]
	v_mfma_i32_16x16x64_i8 v[20:23], v[164:167], v[188:191], v[20:23]
	v_mfma_i32_16x16x64_i8 v[12:15], v[156:159], v[196:199], v[12:15]
	v_mfma_i32_16x16x64_i8 v[8:11], v[164:167], v[196:199], v[8:11]
	v_mfma_i32_16x16x64_i8 v[4:7], v[156:159], v[204:207], v[4:7]
	v_mfma_i32_16x16x64_i8 v[0:3], v[164:167], v[204:207], v[0:3]
	v_mfma_i32_16x16x64_i8 v[44:47], v[160:163], v[184:187], v[44:47]
	v_mfma_i32_16x16x64_i8 v[36:39], v[168:171], v[184:187], v[36:39]
	v_mfma_i32_16x16x64_i8 v[28:31], v[160:163], v[192:195], v[28:31]
	v_mfma_i32_16x16x64_i8 v[20:23], v[168:171], v[192:195], v[20:23]
	v_mfma_i32_16x16x64_i8 v[12:15], v[160:163], v[200:203], v[12:15]
	v_mfma_i32_16x16x64_i8 v[8:11], v[168:171], v[200:203], v[8:11]
	v_mfma_i32_16x16x64_i8 v[4:7], v[160:163], v[208:211], v[4:7]
	v_mfma_i32_16x16x64_i8 v[0:3], v[168:171], v[208:211], v[0:3]
	s_setprio 0
	s_barrier
	s_add_i32 s75, 0, 0x18000
	s_add_i32 s76, 0, 0x1c000
	ds_read_b128 v[140:143], v177 offset:32768
	ds_read_b128 v[144:147], v177 offset:33792
	ds_read_b128 v[148:151], v177 offset:34816
	ds_read_b128 v[152:155], v177 offset:35840
	ds_read_b128 v[156:159], v177 offset:49152
	ds_read_b128 v[160:163], v177 offset:50176
	ds_read_b128 v[164:167], v177 offset:51200
	ds_read_b128 v[168:171], v177 offset:52224
	s_add_u32 s40, s40, 0x80000
	s_addc_u32 s41, s41, 0
	s_mov_b32 m0, s47
	ds_read_b128 v[180:183], v178 offset:32768
	ds_read_b128 v[184:187], v178 offset:33792
	ds_read_b128 v[188:191], v178 offset:34816
	ds_read_b128 v[192:195], v178 offset:35840
	ds_read_b128 v[196:199], v178 offset:36864
	ds_read_b128 v[200:203], v178 offset:37888
	ds_read_b128 v[204:207], v178 offset:38912
	global_load_lds_dwordx4 v128, s[40:41]
	s_mov_b32 m0, s48
	ds_read_b128 v[208:211], v178 offset:39936
	global_load_lds_dwordx4 v132, s[40:41]
	s_waitcnt vmcnt(9) lgkmcnt(0)
	s_barrier
	s_setprio 1
	v_mfma_i32_16x16x64_i8 v[124:127], v[140:143], v[180:183], v[124:127]
	v_mfma_i32_16x16x64_i8 v[120:123], v[148:151], v[180:183], v[120:123]
	v_mfma_i32_16x16x64_i8 v[116:119], v[140:143], v[188:191], v[116:119]
	v_mfma_i32_16x16x64_i8 v[112:115], v[148:151], v[188:191], v[112:115]
	v_mfma_i32_16x16x64_i8 v[104:107], v[140:143], v[196:199], v[104:107]
	v_mfma_i32_16x16x64_i8 v[96:99], v[148:151], v[196:199], v[96:99]
	v_mfma_i32_16x16x64_i8 v[88:91], v[140:143], v[204:207], v[88:91]
	v_mfma_i32_16x16x64_i8 v[80:83], v[148:151], v[204:207], v[80:83]
	v_mfma_i32_16x16x64_i8 v[124:127], v[144:147], v[184:187], v[124:127]
	v_mfma_i32_16x16x64_i8 v[120:123], v[152:155], v[184:187], v[120:123]
	v_mfma_i32_16x16x64_i8 v[116:119], v[144:147], v[192:195], v[116:119]
	v_mfma_i32_16x16x64_i8 v[112:115], v[152:155], v[192:195], v[112:115]
	v_mfma_i32_16x16x64_i8 v[104:107], v[144:147], v[200:203], v[104:107]
	v_mfma_i32_16x16x64_i8 v[96:99], v[152:155], v[200:203], v[96:99]
	v_mfma_i32_16x16x64_i8 v[88:91], v[144:147], v[208:211], v[88:91]
	v_mfma_i32_16x16x64_i8 v[80:83], v[152:155], v[208:211], v[80:83]
	s_setprio 0
	s_setprio 1
	v_mfma_i32_16x16x64_i8 v[108:111], v[156:159], v[180:183], v[108:111]
	v_mfma_i32_16x16x64_i8 v[100:103], v[164:167], v[180:183], v[100:103]
	v_mfma_i32_16x16x64_i8 v[92:95], v[156:159], v[188:191], v[92:95]
	v_mfma_i32_16x16x64_i8 v[84:87], v[164:167], v[188:191], v[84:87]
	v_mfma_i32_16x16x64_i8 v[76:79], v[156:159], v[196:199], v[76:79]
	v_mfma_i32_16x16x64_i8 v[72:75], v[164:167], v[196:199], v[72:75]
	v_mfma_i32_16x16x64_i8 v[68:71], v[156:159], v[204:207], v[68:71]
	v_mfma_i32_16x16x64_i8 v[64:67], v[164:167], v[204:207], v[64:67]
	v_mfma_i32_16x16x64_i8 v[108:111], v[160:163], v[184:187], v[108:111]
	v_mfma_i32_16x16x64_i8 v[100:103], v[168:171], v[184:187], v[100:103]
	v_mfma_i32_16x16x64_i8 v[92:95], v[160:163], v[192:195], v[92:95]
	v_mfma_i32_16x16x64_i8 v[84:87], v[168:171], v[192:195], v[84:87]
	v_mfma_i32_16x16x64_i8 v[76:79], v[160:163], v[200:203], v[76:79]
	v_mfma_i32_16x16x64_i8 v[72:75], v[168:171], v[200:203], v[72:75]
	v_mfma_i32_16x16x64_i8 v[68:71], v[160:163], v[208:211], v[68:71]
	v_mfma_i32_16x16x64_i8 v[64:67], v[168:171], v[208:211], v[64:67]
	s_setprio 0
	s_barrier
	s_add_i32 s40, s75, s42
	v_lshl_add_u64 v[172:173], v[172:173], 0, s[20:21]
	s_mov_b32 m0, s40
	ds_read_b128 v[180:183], v178 offset:49152
	ds_read_b128 v[184:187], v178 offset:50176
	ds_read_b128 v[188:191], v178 offset:51200
	ds_read_b128 v[192:195], v178 offset:52224
	global_load_lds_dwordx4 v[172:173], off
	s_add_i32 m0, s40, 0x2000
	s_add_u32 s38, s38, 0x80080
	v_lshl_add_u64 v[172:173], v[212:213], 0, s[20:21]
	s_addc_u32 s39, s39, 0
	s_add_i32 s40, s76, s42
	global_load_lds_dwordx4 v[172:173], off
	s_mov_b32 m0, s40
	ds_read_b128 v[208:211], v178 offset:56320
	global_load_lds_dwordx4 v130, s[38:39]
	s_add_i32 m0, s40, 0x2000
	ds_read_b128 v[204:207], v178 offset:55296
	global_load_lds_dwordx4 v134, s[38:39]
	v_lshl_add_u64 v[172:173], v[214:215], 0, s[20:21]
	s_mov_b32 m0, s51
	ds_read_b128 v[200:203], v178 offset:54272
	global_load_lds_dwordx4 v[172:173], off
	v_lshl_add_u64 v[172:173], v[216:217], 0, s[20:21]
	s_mov_b32 m0, s52
	ds_read_b128 v[196:199], v178 offset:53248
	global_load_lds_dwordx4 v[172:173], off
	s_waitcnt vmcnt(8) lgkmcnt(0)
	s_barrier
	s_setprio 1
	v_mfma_i32_16x16x64_i8 v[60:63], v[140:143], v[180:183], v[60:63]
	v_mfma_i32_16x16x64_i8 v[56:59], v[148:151], v[180:183], v[56:59]
	v_mfma_i32_16x16x64_i8 v[52:55], v[140:143], v[188:191], v[52:55]
	v_fmaak_f32 v226, v226, v220, 0x4b400000
	v_mfma_i32_16x16x64_i8 v[48:51], v[148:151], v[188:191], v[48:51]
	v_mfma_i32_16x16x64_i8 v[40:43], v[140:143], v[196:199], v[40:43]
	v_mfma_i32_16x16x64_i8 v[32:35], v[148:151], v[196:199], v[32:35]
	v_fmaak_f32 v227, v227, v225, 0x4b400000
	v_mfma_i32_16x16x64_i8 v[24:27], v[140:143], v[204:207], v[24:27]
	v_mfma_i32_16x16x64_i8 v[16:19], v[148:151], v[204:207], v[16:19]
	v_mfma_i32_16x16x64_i8 v[60:63], v[144:147], v[184:187], v[60:63]
	v_fmaak_f32 v228, v228, v252, 0x4b400000
	v_mfma_i32_16x16x64_i8 v[56:59], v[152:155], v[184:187], v[56:59]
	v_mfma_i32_16x16x64_i8 v[52:55], v[144:147], v[192:195], v[52:55]
	v_mfma_i32_16x16x64_i8 v[48:51], v[152:155], v[192:195], v[48:51]
	v_fmaak_f32 v229, v229, v253, 0x4b400000
	v_mfma_i32_16x16x64_i8 v[40:43], v[144:147], v[200:203], v[40:43]
	v_mfma_i32_16x16x64_i8 v[32:35], v[152:155], v[200:203], v[32:35]
	v_mfma_i32_16x16x64_i8 v[24:27], v[144:147], v[208:211], v[24:27]
	v_alignbit_b32 v239, v226, v239, 8
	v_mfma_i32_16x16x64_i8 v[16:19], v[152:155], v[208:211], v[16:19]
	s_setprio 0
	s_setprio 1
	v_mfma_i32_16x16x64_i8 v[44:47], v[156:159], v[180:183], v[44:47]
	v_mfma_i32_16x16x64_i8 v[36:39], v[164:167], v[180:183], v[36:39]
	v_alignbit_b32 v243, v227, v243, 8
	v_mfma_i32_16x16x64_i8 v[28:31], v[156:159], v[188:191], v[28:31]
	v_mfma_i32_16x16x64_i8 v[20:23], v[164:167], v[188:191], v[20:23]
	v_mfma_i32_16x16x64_i8 v[12:15], v[156:159], v[196:199], v[12:15]
	v_alignbit_b32 v247, v228, v247, 8
	v_mfma_i32_16x16x64_i8 v[8:11], v[164:167], v[196:199], v[8:11]
	v_mfma_i32_16x16x64_i8 v[4:7], v[156:159], v[204:207], v[4:7]
	v_mfma_i32_16x16x64_i8 v[0:3], v[164:167], v[204:207], v[0:3]
	v_alignbit_b32 v251, v229, v251, 8
	v_mfma_i32_16x16x64_i8 v[44:47], v[160:163], v[184:187], v[44:47]
	v_mfma_i32_16x16x64_i8 v[36:39], v[168:171], v[184:187], v[36:39]
	v_mfma_i32_16x16x64_i8 v[28:31], v[160:163], v[192:195], v[28:31]
	v_add_u32_e32 v223, 0x4000, v223
	v_mfma_i32_16x16x64_i8 v[20:23], v[168:171], v[192:195], v[20:23]
	v_mfma_i32_16x16x64_i8 v[12:15], v[160:163], v[200:203], v[12:15]
	v_mfma_i32_16x16x64_i8 v[8:11], v[168:171], v[200:203], v[8:11]
	v_mfma_i32_16x16x64_i8 v[4:7], v[160:163], v[208:211], v[4:7]
	v_mfma_i32_16x16x64_i8 v[0:3], v[168:171], v[208:211], v[0:3]
	s_setprio 0
	s_barrier
	s_and_b32 s77, s84, 3
	s_cbranch_scc0 .Lq_mv_L

.Lq_st_j:
	s_waitcnt vmcnt(13) lgkmcnt(0)
	s_barrier
	s_setprio 1
	v_mfma_i32_16x16x64_i8 v[124:127], v[140:143], v[180:183], v[124:127]
	v_mfma_i32_16x16x64_i8 v[120:123], v[148:151], v[180:183], v[120:123]
	v_mfma_i32_16x16x64_i8 v[116:119], v[140:143], v[188:191], v[116:119]
	v_mfma_i32_16x16x64_i8 v[112:115], v[148:151], v[188:191], v[112:115]
	v_mfma_i32_16x16x64_i8 v[104:107], v[140:143], v[196:199], v[104:107]
	v_mfma_i32_16x16x64_i8 v[96:99], v[148:151], v[196:199], v[96:99]
	v_mfma_i32_16x16x64_i8 v[88:91], v[140:143], v[204:207], v[88:91]
	v_mfma_i32_16x16x64_i8 v[80:83], v[148:151], v[204:207], v[80:83]
	v_mfma_i32_16x16x64_i8 v[124:127], v[144:147], v[184:187], v[124:127]
	v_mfma_i32_16x16x64_i8 v[120:123], v[152:155], v[184:187], v[120:123]
	v_mfma_i32_16x16x64_i8 v[116:119], v[144:147], v[192:195], v[116:119]
	v_mfma_i32_16x16x64_i8 v[112:115], v[152:155], v[192:195], v[112:115]
	v_mfma_i32_16x16x64_i8 v[104:107], v[144:147], v[200:203], v[104:107]
	v_mfma_i32_16x16x64_i8 v[96:99], v[152:155], v[200:203], v[96:99]
	v_mfma_i32_16x16x64_i8 v[88:91], v[144:147], v[208:211], v[88:91]
	v_mfma_i32_16x16x64_i8 v[80:83], v[152:155], v[208:211], v[80:83]
	s_setprio 0
	s_setprio 1
	v_mfma_i32_16x16x64_i8 v[108:111], v[156:159], v[180:183], v[108:111]
	v_mfma_i32_16x16x64_i8 v[100:103], v[164:167], v[180:183], v[100:103]
	v_mfma_i32_16x16x64_i8 v[92:95], v[156:159], v[188:191], v[92:95]
	v_mfma_i32_16x16x64_i8 v[84:87], v[164:167], v[188:191], v[84:87]
	v_mfma_i32_16x16x64_i8 v[76:79], v[156:159], v[196:199], v[76:79]
	v_mfma_i32_16x16x64_i8 v[72:75], v[164:167], v[196:199], v[72:75]
	v_mfma_i32_16x16x64_i8 v[68:71], v[156:159], v[204:207], v[68:71]
	v_mfma_i32_16x16x64_i8 v[64:67], v[164:167], v[204:207], v[64:67]
	v_mfma_i32_16x16x64_i8 v[108:111], v[160:163], v[184:187], v[108:111]
	v_mfma_i32_16x16x64_i8 v[100:103], v[168:171], v[184:187], v[100:103]
	v_mfma_i32_16x16x64_i8 v[92:95], v[160:163], v[192:195], v[92:95]
	v_mfma_i32_16x16x64_i8 v[84:87], v[168:171], v[192:195], v[84:87]
	v_mfma_i32_16x16x64_i8 v[76:79], v[160:163], v[200:203], v[76:79]
	v_mfma_i32_16x16x64_i8 v[72:75], v[168:171], v[200:203], v[72:75]
	v_mfma_i32_16x16x64_i8 v[68:71], v[160:163], v[208:211], v[68:71]
	v_mfma_i32_16x16x64_i8 v[64:67], v[168:171], v[208:211], v[64:67]
	s_setprio 0
	s_barrier
	s_add_i32 s75, s55, s42
	v_lshl_add_u64 v[172:173], s[38:39], 0, v[130:131]
	s_mov_b32 m0, s75
	ds_read_b128 v[180:183], v178 offset:16384
	ds_read_b128 v[184:187], v178 offset:17408
	ds_read_b128 v[188:191], v178 offset:18432
	ds_read_b128 v[192:195], v178 offset:19456
	ds_read_b128 v[196:199], v178 offset:20480
	global_load_lds_dwordx4 v130, s[38:39]
	s_add_i32 m0, s75, 0x2000
	s_add_u32 s76, s38, 0x80000
	v_lshl_add_u64 v[212:213], s[38:39], 0, v[134:135]
	s_addc_u32 s77, s39, 0
	s_add_i32 s75, s60, s42
	global_load_lds_dwordx4 v134, s[38:39]
	s_mov_b32 m0, s75
	v_lshl_add_u64 v[216:217], s[40:41], 0, v[132:133]
	global_load_lds_dwordx4 v130, s[76:77]
	s_add_i32 m0, s75, 0x2000
	ds_read_b128 v[208:211], v178 offset:23552
	global_load_lds_dwordx4 v134, s[76:77]
	v_lshl_add_u64 v[214:215], s[40:41], 0, v[128:129]
	s_mov_b32 m0, s45
	ds_read_b128 v[204:207], v178 offset:22528
	global_load_lds_dwordx4 v128, s[40:41]
	s_mov_b32 m0, s46
	ds_read_b128 v[200:203], v178 offset:21504
	global_load_lds_dwordx4 v132, s[40:41]
	s_waitcnt vmcnt(13) lgkmcnt(0)
	s_barrier
	s_setprio 1
	v_mfma_i32_16x16x64_i8 v[60:63], v[140:143], v[180:183], v[60:63]
	v_mfma_i32_16x16x64_i8 v[56:59], v[148:151], v[180:183], v[56:59]
	v_mfma_i32_16x16x64_i8 v[52:55], v[140:143], v[188:191], v[52:55]
	v_mfma_i32_16x16x64_i8 v[48:51], v[148:151], v[188:191], v[48:51]
	v_mfma_i32_16x16x64_i8 v[40:43], v[140:143], v[196:199], v[40:43]
	v_mfma_i32_16x16x64_i8 v[32:35], v[148:151], v[196:199], v[32:35]
	v_mfma_i32_16x16x64_i8 v[24:27], v[140:143], v[204:207], v[24:27]
	v_mfma_i32_16x16x64_i8 v[16:19], v[148:151], v[204:207], v[16:19]
	v_mfma_i32_16x16x64_i8 v[60:63], v[144:147], v[184:187], v[60:63]
	v_mfma_i32_16x16x64_i8 v[56:59], v[152:155], v[184:187], v[56:59]
	v_mfma_i32_16x16x64_i8 v[52:55], v[144:147], v[192:195], v[52:55]
	v_mfma_i32_16x16x64_i8 v[48:51], v[152:155], v[192:195], v[48:51]
	v_mfma_i32_16x16x64_i8 v[40:43], v[144:147], v[200:203], v[40:43]
	v_mfma_i32_16x16x64_i8 v[32:35], v[152:155], v[200:203], v[32:35]
	v_mfma_i32_16x16x64_i8 v[24:27], v[144:147], v[208:211], v[24:27]
	v_mfma_i32_16x16x64_i8 v[16:19], v[152:155], v[208:211], v[16:19]
	s_setprio 0
	s_setprio 1
	v_mfma_i32_16x16x64_i8 v[44:47], v[156:159], v[180:183], v[44:47]
	v_mfma_i32_16x16x64_i8 v[36:39], v[164:167], v[180:183], v[36:39]
	v_mfma_i32_16x16x64_i8 v[28:31], v[156:159], v[188:191], v[28:31]
	v_mfma_i32_16x16x64_i8 v[20:23], v[164:167], v[188:191], v[20:23]
	v_mfma_i32_16x16x64_i8 v[12:15], v[156:159], v[196:199], v[12:15]
	v_mfma_i32_16x16x64_i8 v[8:11], v[164:167], v[196:199], v[8:11]
	v_mfma_i32_16x16x64_i8 v[4:7], v[156:159], v[204:207], v[4:7]
	v_mfma_i32_16x16x64_i8 v[0:3], v[164:167], v[204:207], v[0:3]
	v_mfma_i32_16x16x64_i8 v[44:47], v[160:163], v[184:187], v[44:47]
	v_mfma_i32_16x16x64_i8 v[36:39], v[168:171], v[184:187], v[36:39]
	v_mfma_i32_16x16x64_i8 v[28:31], v[160:163], v[192:195], v[28:31]
	v_mfma_i32_16x16x64_i8 v[20:23], v[168:171], v[192:195], v[20:23]
	v_mfma_i32_16x16x64_i8 v[12:15], v[160:163], v[200:203], v[12:15]
	v_mfma_i32_16x16x64_i8 v[8:11], v[168:171], v[200:203], v[8:11]
	v_mfma_i32_16x16x64_i8 v[4:7], v[160:163], v[208:211], v[4:7]
	v_mfma_i32_16x16x64_i8 v[0:3], v[168:171], v[208:211], v[0:3]
	s_setprio 0
	s_barrier
	s_add_i32 s75, 0, 0x18000
	s_add_i32 s76, 0, 0x1c000
	ds_read_b128 v[140:143], v177 offset:32768
	ds_read_b128 v[144:147], v177 offset:33792
	ds_read_b128 v[148:151], v177 offset:34816
	ds_read_b128 v[152:155], v177 offset:35840
	ds_read_b128 v[156:159], v177 offset:49152
	ds_read_b128 v[160:163], v177 offset:50176
	ds_read_b128 v[164:167], v177 offset:51200
	ds_read_b128 v[168:171], v177 offset:52224
	s_add_u32 s40, s40, 0x80000
	s_addc_u32 s41, s41, 0
	s_mov_b32 m0, s47
	ds_read_b128 v[180:183], v178 offset:32768
	ds_read_b128 v[184:187], v178 offset:33792
	ds_read_b128 v[188:191], v178 offset:34816
	ds_read_b128 v[192:195], v178 offset:35840
	ds_read_b128 v[196:199], v178 offset:36864
	ds_read_b128 v[200:203], v178 offset:37888
	ds_read_b128 v[204:207], v178 offset:38912
	global_load_lds_dwordx4 v128, s[40:41]
	s_mov_b32 m0, s48
	ds_read_b128 v[208:211], v178 offset:39936
	global_load_lds_dwordx4 v132, s[40:41]
	s_waitcnt vmcnt(13) lgkmcnt(0)
	s_barrier
	s_setprio 1
	v_mfma_i32_16x16x64_i8 v[124:127], v[140:143], v[180:183], v[124:127]
	v_mfma_i32_16x16x64_i8 v[120:123], v[148:151], v[180:183], v[120:123]
	v_mfma_i32_16x16x64_i8 v[116:119], v[140:143], v[188:191], v[116:119]
	v_mfma_i32_16x16x64_i8 v[112:115], v[148:151], v[188:191], v[112:115]
	v_mfma_i32_16x16x64_i8 v[104:107], v[140:143], v[196:199], v[104:107]
	v_mfma_i32_16x16x64_i8 v[96:99], v[148:151], v[196:199], v[96:99]
	v_mfma_i32_16x16x64_i8 v[88:91], v[140:143], v[204:207], v[88:91]
	v_mfma_i32_16x16x64_i8 v[80:83], v[148:151], v[204:207], v[80:83]
	v_mfma_i32_16x16x64_i8 v[124:127], v[144:147], v[184:187], v[124:127]
	v_mfma_i32_16x16x64_i8 v[120:123], v[152:155], v[184:187], v[120:123]
	v_mfma_i32_16x16x64_i8 v[116:119], v[144:147], v[192:195], v[116:119]
	v_mfma_i32_16x16x64_i8 v[112:115], v[152:155], v[192:195], v[112:115]
	v_mfma_i32_16x16x64_i8 v[104:107], v[144:147], v[200:203], v[104:107]
	v_mfma_i32_16x16x64_i8 v[96:99], v[152:155], v[200:203], v[96:99]
	v_mfma_i32_16x16x64_i8 v[88:91], v[144:147], v[208:211], v[88:91]
	v_mfma_i32_16x16x64_i8 v[80:83], v[152:155], v[208:211], v[80:83]
	s_setprio 0
	s_setprio 1
	v_mfma_i32_16x16x64_i8 v[108:111], v[156:159], v[180:183], v[108:111]
	v_mfma_i32_16x16x64_i8 v[100:103], v[164:167], v[180:183], v[100:103]
	v_mfma_i32_16x16x64_i8 v[92:95], v[156:159], v[188:191], v[92:95]
	v_mfma_i32_16x16x64_i8 v[84:87], v[164:167], v[188:191], v[84:87]
	v_mfma_i32_16x16x64_i8 v[76:79], v[156:159], v[196:199], v[76:79]
	v_mfma_i32_16x16x64_i8 v[72:75], v[164:167], v[196:199], v[72:75]
	v_mfma_i32_16x16x64_i8 v[68:71], v[156:159], v[204:207], v[68:71]
	v_mfma_i32_16x16x64_i8 v[64:67], v[164:167], v[204:207], v[64:67]
	v_mfma_i32_16x16x64_i8 v[108:111], v[160:163], v[184:187], v[108:111]
	v_mfma_i32_16x16x64_i8 v[100:103], v[168:171], v[184:187], v[100:103]
	v_mfma_i32_16x16x64_i8 v[92:95], v[160:163], v[192:195], v[92:95]
	v_mfma_i32_16x16x64_i8 v[84:87], v[168:171], v[192:195], v[84:87]
	v_mfma_i32_16x16x64_i8 v[76:79], v[160:163], v[200:203], v[76:79]
	v_mfma_i32_16x16x64_i8 v[72:75], v[168:171], v[200:203], v[72:75]
	v_mfma_i32_16x16x64_i8 v[68:71], v[160:163], v[208:211], v[68:71]
	v_mfma_i32_16x16x64_i8 v[64:67], v[168:171], v[208:211], v[64:67]
	s_setprio 0
	s_barrier
	s_add_i32 s40, s75, s42
	v_lshl_add_u64 v[172:173], v[172:173], 0, s[20:21]
	s_mov_b32 m0, s40
	ds_read_b128 v[180:183], v178 offset:49152
	ds_read_b128 v[184:187], v178 offset:50176
	ds_read_b128 v[188:191], v178 offset:51200
	ds_read_b128 v[192:195], v178 offset:52224
	global_load_lds_dwordx4 v[172:173], off
	s_add_i32 m0, s40, 0x2000
	s_add_u32 s38, s38, 0x80080
	v_lshl_add_u64 v[172:173], v[212:213], 0, s[20:21]
	s_addc_u32 s39, s39, 0
	s_add_i32 s40, s76, s42
	global_load_lds_dwordx4 v[172:173], off
	s_mov_b32 m0, s40
	ds_read_b128 v[208:211], v178 offset:56320
	global_load_lds_dwordx4 v130, s[38:39]
	s_add_i32 m0, s40, 0x2000
	ds_read_b128 v[204:207], v178 offset:55296
	global_load_lds_dwordx4 v134, s[38:39]
	v_lshl_add_u64 v[172:173], v[214:215], 0, s[20:21]
	s_mov_b32 m0, s51
	ds_read_b128 v[200:203], v178 offset:54272
	global_load_lds_dwordx4 v[172:173], off
	v_lshl_add_u64 v[172:173], v[216:217], 0, s[20:21]
	s_mov_b32 m0, s52
	ds_read_b128 v[196:199], v178 offset:53248
	global_load_lds_dwordx4 v[172:173], off
	s_waitcnt vmcnt(8) lgkmcnt(0)
	s_barrier
	s_setprio 1
	v_mfma_i32_16x16x64_i8 v[60:63], v[140:143], v[180:183], v[60:63]
	v_mfma_i32_16x16x64_i8 v[56:59], v[148:151], v[180:183], v[56:59]
	v_mfma_i32_16x16x64_i8 v[52:55], v[140:143], v[188:191], v[52:55]
	v_fmaak_f32 v226, v226, v220, 0x4b400000
	v_mfma_i32_16x16x64_i8 v[48:51], v[148:151], v[188:191], v[48:51]
	v_mfma_i32_16x16x64_i8 v[40:43], v[140:143], v[196:199], v[40:43]
	v_mfma_i32_16x16x64_i8 v[32:35], v[148:151], v[196:199], v[32:35]
	v_fmaak_f32 v227, v227, v225, 0x4b400000
	v_mfma_i32_16x16x64_i8 v[24:27], v[140:143], v[204:207], v[24:27]
	v_mfma_i32_16x16x64_i8 v[16:19], v[148:151], v[204:207], v[16:19]
	v_mfma_i32_16x16x64_i8 v[60:63], v[144:147], v[184:187], v[60:63]
	v_fmaak_f32 v228, v228, v252, 0x4b400000
	v_mfma_i32_16x16x64_i8 v[56:59], v[152:155], v[184:187], v[56:59]
	v_mfma_i32_16x16x64_i8 v[52:55], v[144:147], v[192:195], v[52:55]
	v_mfma_i32_16x16x64_i8 v[48:51], v[152:155], v[192:195], v[48:51]
	v_fmaak_f32 v229, v229, v253, 0x4b400000
	v_mfma_i32_16x16x64_i8 v[40:43], v[144:147], v[200:203], v[40:43]
	v_mfma_i32_16x16x64_i8 v[32:35], v[152:155], v[200:203], v[32:35]
	v_mfma_i32_16x16x64_i8 v[24:27], v[144:147], v[208:211], v[24:27]
	v_alignbit_b32 v239, v226, v239, 8
	v_mfma_i32_16x16x64_i8 v[16:19], v[152:155], v[208:211], v[16:19]
	s_setprio 0
	s_setprio 1
	v_mfma_i32_16x16x64_i8 v[44:47], v[156:159], v[180:183], v[44:47]
	v_mfma_i32_16x16x64_i8 v[36:39], v[164:167], v[180:183], v[36:39]
	v_alignbit_b32 v243, v227, v243, 8
	v_mfma_i32_16x16x64_i8 v[28:31], v[156:159], v[188:191], v[28:31]
	v_mfma_i32_16x16x64_i8 v[20:23], v[164:167], v[188:191], v[20:23]
	v_mfma_i32_16x16x64_i8 v[12:15], v[156:159], v[196:199], v[12:15]
	v_alignbit_b32 v247, v228, v247, 8
	v_mfma_i32_16x16x64_i8 v[8:11], v[164:167], v[196:199], v[8:11]
	v_mfma_i32_16x16x64_i8 v[4:7], v[156:159], v[204:207], v[4:7]
	v_mfma_i32_16x16x64_i8 v[0:3], v[164:167], v[204:207], v[0:3]
	v_alignbit_b32 v251, v229, v251, 8
	v_mfma_i32_16x16x64_i8 v[44:47], v[160:163], v[184:187], v[44:47]
	v_mfma_i32_16x16x64_i8 v[36:39], v[168:171], v[184:187], v[36:39]
	v_mfma_i32_16x16x64_i8 v[28:31], v[160:163], v[192:195], v[28:31]
	v_add_u32_e32 v223, 0x4000, v223
	v_mfma_i32_16x16x64_i8 v[20:23], v[168:171], v[192:195], v[20:23]
	v_mfma_i32_16x16x64_i8 v[12:15], v[160:163], v[200:203], v[12:15]
	v_mfma_i32_16x16x64_i8 v[8:11], v[168:171], v[200:203], v[8:11]
	v_mfma_i32_16x16x64_i8 v[4:7], v[160:163], v[208:211], v[4:7]
	v_mfma_i32_16x16x64_i8 v[0:3], v[168:171], v[208:211], v[0:3]
	s_setprio 0
	s_barrier
	s_cmp_eq_u32 s32, 0
	s_cbranch_scc1 .Lq_mvx_ST
	s_and_b32 s77, s84, 3
	s_cbranch_scc0 .Lq_mv_ST

.LBB0_1474:
	s_add_i32 s75, s48, 2
	s_add_u32 s46, s44, 0x100
	s_addc_u32 s47, s45, 0
	s_cmp_eq_u32 s72, s48
	s_cselect_b32 s51, s41, s47
	s_cselect_b32 s50, s40, s46
	ds_read_b128 v[140:143], v184
	ds_read_b128 v[144:147], v184 offset:1024
	ds_read_b128 v[148:151], v184 offset:2048
	ds_read_b128 v[152:155], v184 offset:3072
	ds_read_b128 v[156:159], v184 offset:16384
	ds_read_b128 v[160:163], v184 offset:17408
	ds_read_b128 v[164:167], v184 offset:18432
	ds_read_b128 v[168:171], v184 offset:19456
	s_cselect_b32 s48, s42, s73
	s_cselect_b32 s49, s43, s74
	s_add_i32 m0, s54, 0xc000
	ds_read_b128 v[172:175], v186
	ds_read_b128 v[176:179], v186 offset:1024
	ds_read_b128 v[188:191], v186 offset:2048
	ds_read_b128 v[192:195], v186 offset:3072
	ds_read_b128 v[196:199], v186 offset:4096
	ds_read_b128 v[200:203], v186 offset:5120
	ds_read_b128 v[204:207], v186 offset:6144
	global_load_lds_dwordx4 v136, s[44:45]
	s_add_i32 m0, s54, 0xe000
	ds_read_b128 v[208:211], v186 offset:7168
	global_load_lds_dwordx4 v138, s[44:45]
	s_waitcnt vmcnt(8) lgkmcnt(0)
	s_barrier
	s_setprio 1
	v_mfma_i32_16x16x64_i8 v[124:127], v[140:143], v[172:175], v[124:127]
	v_mfma_i32_16x16x64_i8 v[120:123], v[148:151], v[172:175], v[120:123]
	v_mfma_i32_16x16x64_i8 v[116:119], v[140:143], v[188:191], v[116:119]
	v_mfma_i32_16x16x64_i8 v[112:115], v[148:151], v[188:191], v[112:115]
	v_mfma_i32_16x16x64_i8 v[104:107], v[140:143], v[196:199], v[104:107]
	v_mfma_i32_16x16x64_i8 v[96:99], v[148:151], v[196:199], v[96:99]
	v_mfma_i32_16x16x64_i8 v[88:91], v[140:143], v[204:207], v[88:91]
	v_mfma_i32_16x16x64_i8 v[80:83], v[148:151], v[204:207], v[80:83]
	v_mfma_i32_16x16x64_i8 v[124:127], v[144:147], v[176:179], v[124:127]
	v_mfma_i32_16x16x64_i8 v[120:123], v[152:155], v[176:179], v[120:123]
	v_mfma_i32_16x16x64_i8 v[116:119], v[144:147], v[192:195], v[116:119]
	v_mfma_i32_16x16x64_i8 v[112:115], v[152:155], v[192:195], v[112:115]
	v_mfma_i32_16x16x64_i8 v[104:107], v[144:147], v[200:203], v[104:107]
	v_mfma_i32_16x16x64_i8 v[96:99], v[152:155], v[200:203], v[96:99]
	v_mfma_i32_16x16x64_i8 v[88:91], v[144:147], v[208:211], v[88:91]
	v_mfma_i32_16x16x64_i8 v[80:83], v[152:155], v[208:211], v[80:83]
	s_setprio 0
	s_setprio 1
	v_mfma_i32_16x16x64_i8 v[108:111], v[156:159], v[172:175], v[108:111]
	v_mfma_i32_16x16x64_i8 v[100:103], v[164:167], v[172:175], v[100:103]
	v_mfma_i32_16x16x64_i8 v[92:95], v[156:159], v[188:191], v[92:95]
	v_mfma_i32_16x16x64_i8 v[84:87], v[164:167], v[188:191], v[84:87]
	v_mfma_i32_16x16x64_i8 v[76:79], v[156:159], v[196:199], v[76:79]
	v_mfma_i32_16x16x64_i8 v[72:75], v[164:167], v[196:199], v[72:75]
	v_mfma_i32_16x16x64_i8 v[68:71], v[156:159], v[204:207], v[68:71]
	v_mfma_i32_16x16x64_i8 v[64:67], v[164:167], v[204:207], v[64:67]
	v_mfma_i32_16x16x64_i8 v[108:111], v[160:163], v[176:179], v[108:111]
	v_mfma_i32_16x16x64_i8 v[100:103], v[168:171], v[176:179], v[100:103]
	v_mfma_i32_16x16x64_i8 v[92:95], v[160:163], v[192:195], v[92:95]
	v_mfma_i32_16x16x64_i8 v[84:87], v[168:171], v[192:195], v[84:87]
	v_mfma_i32_16x16x64_i8 v[76:79], v[160:163], v[200:203], v[76:79]
	v_mfma_i32_16x16x64_i8 v[72:75], v[168:171], v[200:203], v[72:75]
	v_mfma_i32_16x16x64_i8 v[68:71], v[160:163], v[208:211], v[68:71]
	v_mfma_i32_16x16x64_i8 v[64:67], v[168:171], v[208:211], v[64:67]
	s_setprio 0
	s_barrier
	s_add_i32 s44, s66, s53
	s_mov_b32 m0, s44
	ds_read_b128 v[172:175], v186 offset:16384
	ds_read_b128 v[176:179], v186 offset:17408
	ds_read_b128 v[188:191], v186 offset:18432
	ds_read_b128 v[192:195], v186 offset:19456
	global_load_lds_dwordx4 v130, s[48:49]
	s_add_i32 m0, s44, 0x2000
	s_add_u32 s44, s48, 0x158000
	s_addc_u32 s45, s49, 0
	s_add_i32 s76, s67, s53
	global_load_lds_dwordx4 v134, s[48:49]
	s_mov_b32 m0, s76
	ds_read_b128 v[208:211], v186 offset:23552
	global_load_lds_dwordx4 v130, s[44:45]
	s_add_i32 m0, s76, 0x2000
	ds_read_b128 v[204:207], v186 offset:22528
	global_load_lds_dwordx4 v134, s[44:45]
	s_mov_b32 m0, s54
	ds_read_b128 v[200:203], v186 offset:21504
	global_load_lds_dwordx4 v128, s[50:51]
	s_mov_b32 m0, s55
	ds_read_b128 v[196:199], v186 offset:20480
	global_load_lds_dwordx4 v132, s[50:51]
	s_waitcnt vmcnt(8) lgkmcnt(0)
	s_barrier
	s_setprio 1
	v_mfma_i32_16x16x64_i8 v[60:63], v[140:143], v[172:175], v[60:63]
	v_mfma_i32_16x16x64_i8 v[56:59], v[148:151], v[172:175], v[56:59]
	v_mfma_i32_16x16x64_i8 v[52:55], v[140:143], v[188:191], v[52:55]
	v_mfma_i32_16x16x64_i8 v[48:51], v[148:151], v[188:191], v[48:51]
	v_mfma_i32_16x16x64_i8 v[40:43], v[140:143], v[196:199], v[40:43]
	v_mfma_i32_16x16x64_i8 v[32:35], v[148:151], v[196:199], v[32:35]
	v_mfma_i32_16x16x64_i8 v[24:27], v[140:143], v[204:207], v[24:27]
	v_mfma_i32_16x16x64_i8 v[16:19], v[148:151], v[204:207], v[16:19]
	v_mfma_i32_16x16x64_i8 v[60:63], v[144:147], v[176:179], v[60:63]
	v_mfma_i32_16x16x64_i8 v[56:59], v[152:155], v[176:179], v[56:59]
	v_mfma_i32_16x16x64_i8 v[52:55], v[144:147], v[192:195], v[52:55]
	v_mfma_i32_16x16x64_i8 v[48:51], v[152:155], v[192:195], v[48:51]
	v_mfma_i32_16x16x64_i8 v[40:43], v[144:147], v[200:203], v[40:43]
	v_mfma_i32_16x16x64_i8 v[32:35], v[152:155], v[200:203], v[32:35]
	v_mfma_i32_16x16x64_i8 v[24:27], v[144:147], v[208:211], v[24:27]
	v_mfma_i32_16x16x64_i8 v[16:19], v[152:155], v[208:211], v[16:19]
	s_setprio 0
	s_setprio 1
	v_mfma_i32_16x16x64_i8 v[44:47], v[156:159], v[172:175], v[44:47]
	v_mfma_i32_16x16x64_i8 v[36:39], v[164:167], v[172:175], v[36:39]
	v_mfma_i32_16x16x64_i8 v[28:31], v[156:159], v[188:191], v[28:31]
	v_mfma_i32_16x16x64_i8 v[20:23], v[164:167], v[188:191], v[20:23]
	v_mfma_i32_16x16x64_i8 v[12:15], v[156:159], v[196:199], v[12:15]
	v_mfma_i32_16x16x64_i8 v[8:11], v[164:167], v[196:199], v[8:11]
	v_mfma_i32_16x16x64_i8 v[4:7], v[156:159], v[204:207], v[4:7]
	v_mfma_i32_16x16x64_i8 v[0:3], v[164:167], v[204:207], v[0:3]
	v_mfma_i32_16x16x64_i8 v[44:47], v[160:163], v[176:179], v[44:47]
	v_mfma_i32_16x16x64_i8 v[36:39], v[168:171], v[176:179], v[36:39]
	v_mfma_i32_16x16x64_i8 v[28:31], v[160:163], v[192:195], v[28:31]
	v_mfma_i32_16x16x64_i8 v[20:23], v[168:171], v[192:195], v[20:23]
	v_mfma_i32_16x16x64_i8 v[12:15], v[160:163], v[200:203], v[12:15]
	v_mfma_i32_16x16x64_i8 v[8:11], v[168:171], v[200:203], v[8:11]
	v_mfma_i32_16x16x64_i8 v[4:7], v[160:163], v[208:211], v[4:7]
	v_mfma_i32_16x16x64_i8 v[0:3], v[168:171], v[208:211], v[0:3]
	s_setprio 0
	s_barrier
	s_add_i32 s76, 0, 0x18000
	s_add_i32 s77, 0, 0x1c000
	ds_read_b128 v[140:143], v184 offset:32768
	ds_read_b128 v[144:147], v184 offset:33792
	ds_read_b128 v[148:151], v184 offset:34816
	ds_read_b128 v[152:155], v184 offset:35840
	ds_read_b128 v[156:159], v184 offset:49152
	ds_read_b128 v[160:163], v184 offset:50176
	ds_read_b128 v[164:167], v184 offset:51200
	ds_read_b128 v[168:171], v184 offset:52224
	s_add_u32 s44, s50, 0x158000
	s_addc_u32 s45, s51, 0
	s_mov_b32 m0, s60
	ds_read_b128 v[172:175], v186 offset:32768
	ds_read_b128 v[176:179], v186 offset:33792
	ds_read_b128 v[188:191], v186 offset:34816
	ds_read_b128 v[192:195], v186 offset:35840
	ds_read_b128 v[196:199], v186 offset:36864
	ds_read_b128 v[200:203], v186 offset:37888
	ds_read_b128 v[204:207], v186 offset:38912
	global_load_lds_dwordx4 v128, s[44:45]
	s_mov_b32 m0, s61
	ds_read_b128 v[208:211], v186 offset:39936
	global_load_lds_dwordx4 v132, s[44:45]
	s_waitcnt vmcnt(8) lgkmcnt(0)
	s_barrier
	s_setprio 1
	v_mfma_i32_16x16x64_i8 v[124:127], v[140:143], v[172:175], v[124:127]
	v_mfma_i32_16x16x64_i8 v[120:123], v[148:151], v[172:175], v[120:123]
	v_mfma_i32_16x16x64_i8 v[116:119], v[140:143], v[188:191], v[116:119]
	v_mfma_i32_16x16x64_i8 v[112:115], v[148:151], v[188:191], v[112:115]
	v_mfma_i32_16x16x64_i8 v[104:107], v[140:143], v[196:199], v[104:107]
	v_mfma_i32_16x16x64_i8 v[96:99], v[148:151], v[196:199], v[96:99]
	v_mfma_i32_16x16x64_i8 v[88:91], v[140:143], v[204:207], v[88:91]
	v_mfma_i32_16x16x64_i8 v[80:83], v[148:151], v[204:207], v[80:83]
	v_mfma_i32_16x16x64_i8 v[124:127], v[144:147], v[176:179], v[124:127]
	v_mfma_i32_16x16x64_i8 v[120:123], v[152:155], v[176:179], v[120:123]
	v_mfma_i32_16x16x64_i8 v[116:119], v[144:147], v[192:195], v[116:119]
	v_mfma_i32_16x16x64_i8 v[112:115], v[152:155], v[192:195], v[112:115]
	v_mfma_i32_16x16x64_i8 v[104:107], v[144:147], v[200:203], v[104:107]
	v_mfma_i32_16x16x64_i8 v[96:99], v[152:155], v[200:203], v[96:99]
	v_mfma_i32_16x16x64_i8 v[88:91], v[144:147], v[208:211], v[88:91]
	v_mfma_i32_16x16x64_i8 v[80:83], v[152:155], v[208:211], v[80:83]
	s_setprio 0
	s_setprio 1
	v_mfma_i32_16x16x64_i8 v[108:111], v[156:159], v[172:175], v[108:111]
	v_mfma_i32_16x16x64_i8 v[100:103], v[164:167], v[172:175], v[100:103]
	v_mfma_i32_16x16x64_i8 v[92:95], v[156:159], v[188:191], v[92:95]
	v_mfma_i32_16x16x64_i8 v[84:87], v[164:167], v[188:191], v[84:87]
	v_mfma_i32_16x16x64_i8 v[76:79], v[156:159], v[196:199], v[76:79]
	v_mfma_i32_16x16x64_i8 v[72:75], v[164:167], v[196:199], v[72:75]
	v_mfma_i32_16x16x64_i8 v[68:71], v[156:159], v[204:207], v[68:71]
	v_mfma_i32_16x16x64_i8 v[64:67], v[164:167], v[204:207], v[64:67]
	v_mfma_i32_16x16x64_i8 v[108:111], v[160:163], v[176:179], v[108:111]
	v_mfma_i32_16x16x64_i8 v[100:103], v[168:171], v[176:179], v[100:103]
	v_mfma_i32_16x16x64_i8 v[92:95], v[160:163], v[192:195], v[92:95]
	v_mfma_i32_16x16x64_i8 v[84:87], v[168:171], v[192:195], v[84:87]
	v_mfma_i32_16x16x64_i8 v[76:79], v[160:163], v[200:203], v[76:79]
	v_mfma_i32_16x16x64_i8 v[72:75], v[168:171], v[200:203], v[72:75]
	v_mfma_i32_16x16x64_i8 v[68:71], v[160:163], v[208:211], v[68:71]
	v_mfma_i32_16x16x64_i8 v[64:67], v[168:171], v[208:211], v[64:67]
	s_setprio 0
	s_barrier
	s_add_u32 s98, s48, s18
	s_addc_u32 s99, s49, s19
	s_add_u32 s100, s50, s18
	s_addc_u32 s101, s51, s19
	s_add_i32 s44, s76, s53
	s_mov_b32 m0, s44
	ds_read_b128 v[172:175], v186 offset:49152
	ds_read_b128 v[176:179], v186 offset:50176
	ds_read_b128 v[188:191], v186 offset:51200
	ds_read_b128 v[192:195], v186 offset:52224
	global_load_lds_dwordx4 v130, s[98:99]
	s_add_i32 m0, s44, 0x2000
	s_add_u32 s44, s48, 0x158080
	s_addc_u32 s45, s49, 0
	s_add_i32 s48, s77, s53
	global_load_lds_dwordx4 v134, s[98:99]
	s_mov_b32 m0, s48
	ds_read_b128 v[208:211], v186 offset:56320
	global_load_lds_dwordx4 v130, s[44:45]
	s_add_i32 m0, s48, 0x2000
	ds_read_b128 v[204:207], v186 offset:55296
	global_load_lds_dwordx4 v134, s[44:45]
	s_mov_b32 m0, s64
	ds_read_b128 v[200:203], v186 offset:54272
	global_load_lds_dwordx4 v128, s[100:101]
	s_mov_b32 m0, s65
	ds_read_b128 v[196:199], v186 offset:53248
	global_load_lds_dwordx4 v132, s[100:101]
	s_waitcnt vmcnt(8) lgkmcnt(0)
	s_barrier
	s_setprio 1
	v_mfma_i32_16x16x64_i8 v[60:63], v[140:143], v[172:175], v[60:63]
	v_mfma_i32_16x16x64_i8 v[56:59], v[148:151], v[172:175], v[56:59]
	v_mfma_i32_16x16x64_i8 v[52:55], v[140:143], v[188:191], v[52:55]
	v_mfma_i32_16x16x64_i8 v[48:51], v[148:151], v[188:191], v[48:51]
	v_mfma_i32_16x16x64_i8 v[40:43], v[140:143], v[196:199], v[40:43]
	v_mfma_i32_16x16x64_i8 v[32:35], v[148:151], v[196:199], v[32:35]
	v_mfma_i32_16x16x64_i8 v[24:27], v[140:143], v[204:207], v[24:27]
	v_mfma_i32_16x16x64_i8 v[16:19], v[148:151], v[204:207], v[16:19]
	v_mfma_i32_16x16x64_i8 v[60:63], v[144:147], v[176:179], v[60:63]
	v_mfma_i32_16x16x64_i8 v[56:59], v[152:155], v[176:179], v[56:59]
	v_mfma_i32_16x16x64_i8 v[52:55], v[144:147], v[192:195], v[52:55]
	v_mfma_i32_16x16x64_i8 v[48:51], v[152:155], v[192:195], v[48:51]
	v_mfma_i32_16x16x64_i8 v[40:43], v[144:147], v[200:203], v[40:43]
	v_mfma_i32_16x16x64_i8 v[32:35], v[152:155], v[200:203], v[32:35]
	v_mfma_i32_16x16x64_i8 v[24:27], v[144:147], v[208:211], v[24:27]
	v_mfma_i32_16x16x64_i8 v[16:19], v[152:155], v[208:211], v[16:19]
	s_setprio 0
	s_setprio 1
	v_mfma_i32_16x16x64_i8 v[44:47], v[156:159], v[172:175], v[44:47]
	v_mfma_i32_16x16x64_i8 v[36:39], v[164:167], v[172:175], v[36:39]
	v_mfma_i32_16x16x64_i8 v[28:31], v[156:159], v[188:191], v[28:31]
	v_mfma_i32_16x16x64_i8 v[20:23], v[164:167], v[188:191], v[20:23]
	v_mfma_i32_16x16x64_i8 v[12:15], v[156:159], v[196:199], v[12:15]
	v_mfma_i32_16x16x64_i8 v[8:11], v[164:167], v[196:199], v[8:11]
	v_mfma_i32_16x16x64_i8 v[4:7], v[156:159], v[204:207], v[4:7]
	v_mfma_i32_16x16x64_i8 v[0:3], v[164:167], v[204:207], v[0:3]
	v_mfma_i32_16x16x64_i8 v[44:47], v[160:163], v[176:179], v[44:47]
	v_mfma_i32_16x16x64_i8 v[36:39], v[168:171], v[176:179], v[36:39]
	v_mfma_i32_16x16x64_i8 v[28:31], v[160:163], v[192:195], v[28:31]
	v_mfma_i32_16x16x64_i8 v[20:23], v[168:171], v[192:195], v[20:23]
	v_mfma_i32_16x16x64_i8 v[12:15], v[160:163], v[200:203], v[12:15]
	v_mfma_i32_16x16x64_i8 v[8:11], v[168:171], v[200:203], v[8:11]
	v_mfma_i32_16x16x64_i8 v[4:7], v[160:163], v[208:211], v[4:7]
	v_mfma_i32_16x16x64_i8 v[0:3], v[168:171], v[208:211], v[0:3]
	s_setprio 0
	s_barrier
	s_add_u32 s73, s73, 0x100
	s_addc_u32 s74, s74, 0
	s_cmp_ge_i32 s75, s71
	s_mov_b64 s[44:45], s[46:47]
	s_mov_b32 s48, s75
	s_cbranch_scc0 .LBB0_1474
	v_cvt_f32_i32_e32 v140, v124
	v_cvt_f32_i32_e32 v141, v125
	v_cvt_f32_i32_e32 v124, v126
	v_cvt_f32_i32_e32 v125, v127
	v_cvt_f32_i32_e32 v142, v120
	v_cvt_f32_i32_e32 v143, v121
	v_cvt_f32_i32_e32 v126, v122
	v_cvt_f32_i32_e32 v127, v123
	v_cvt_f32_i32_e32 v146, v108
	v_cvt_f32_i32_e32 v147, v109
	v_cvt_f32_i32_e32 v120, v110
	v_cvt_f32_i32_e32 v121, v111
	v_cvt_f32_i32_e32 v148, v100
	v_cvt_f32_i32_e32 v149, v101
	v_cvt_f32_i32_e32 v122, v102
	v_cvt_f32_i32_e32 v123, v103
	v_cvt_f32_i32_e32 v144, v116
	v_cvt_f32_i32_e32 v145, v117
	v_cvt_f32_i32_e32 v116, v118
	v_cvt_f32_i32_e32 v117, v119
	v_cvt_f32_i32_e32 v118, v112
	v_cvt_f32_i32_e32 v119, v113
	v_cvt_f32_i32_e32 v112, v114
	v_cvt_f32_i32_e32 v113, v115
	v_cvt_f32_i32_e32 v152, v92
	v_cvt_f32_i32_e32 v153, v93
	v_cvt_f32_i32_e32 v100, v94
	v_cvt_f32_i32_e32 v101, v95
	v_cvt_f32_i32_e32 v156, v84
	v_cvt_f32_i32_e32 v157, v85
	v_cvt_f32_i32_e32 v102, v86
	v_cvt_f32_i32_e32 v103, v87
	v_cvt_f32_i32_e32 v114, v104
	v_cvt_f32_i32_e32 v115, v105
	v_cvt_f32_i32_e32 v86, v106
	v_cvt_f32_i32_e32 v87, v107
	v_cvt_f32_i32_e32 v150, v96
	v_cvt_f32_i32_e32 v151, v97
	v_cvt_f32_i32_e32 v92, v98
	v_cvt_f32_i32_e32 v93, v99
	v_cvt_f32_i32_e32 v160, v76
	v_cvt_f32_i32_e32 v161, v77
	v_cvt_f32_i32_e32 v84, v78
	v_cvt_f32_i32_e32 v85, v79
	v_cvt_f32_i32_e32 v162, v72
	v_cvt_f32_i32_e32 v163, v73
	v_cvt_f32_i32_e32 v94, v74
	v_cvt_f32_i32_e32 v95, v75
	v_cvt_f32_i32_e32 v154, v88
	v_cvt_f32_i32_e32 v155, v89
	v_cvt_f32_i32_e32 v78, v90
	v_cvt_f32_i32_e32 v79, v91
	v_cvt_f32_i32_e32 v158, v80
	v_cvt_f32_i32_e32 v159, v81
	v_cvt_f32_i32_e32 v80, v82
	v_cvt_f32_i32_e32 v81, v83
	v_cvt_f32_i32_e32 v164, v68
	v_cvt_f32_i32_e32 v165, v69
	v_cvt_f32_i32_e32 v76, v70
	v_cvt_f32_i32_e32 v77, v71
	v_cvt_f32_i32_e32 v166, v64
	v_cvt_f32_i32_e32 v167, v65
	v_cvt_f32_i32_e32 v82, v66
	v_cvt_f32_i32_e32 v83, v67
	v_cvt_f32_i32_e32 v70, v60
	v_cvt_f32_i32_e32 v71, v61
	v_cvt_f32_i32_e32 v74, v62
	v_cvt_f32_i32_e32 v75, v63
	v_cvt_f32_i32_e32 v68, v56
	v_cvt_f32_i32_e32 v69, v57
	v_cvt_f32_i32_e32 v72, v58
	v_cvt_f32_i32_e32 v73, v59
	v_cvt_f32_i32_e32 v62, v44
	v_cvt_f32_i32_e32 v63, v45
	v_cvt_f32_i32_e32 v66, v46
	v_cvt_f32_i32_e32 v67, v47
	v_cvt_f32_i32_e32 v60, v36
	v_cvt_f32_i32_e32 v61, v37
	v_cvt_f32_i32_e32 v64, v38
	v_cvt_f32_i32_e32 v65, v39
	v_cvt_f32_i32_e32 v56, v52
	v_cvt_f32_i32_e32 v57, v53
	v_cvt_f32_i32_e32 v58, v54
	v_cvt_f32_i32_e32 v59, v55
	v_cvt_f32_i32_e32 v52, v48
	v_cvt_f32_i32_e32 v53, v49
	v_cvt_f32_i32_e32 v54, v50
	v_cvt_f32_i32_e32 v55, v51
	v_cvt_f32_i32_e32 v46, v28
	v_cvt_f32_i32_e32 v47, v29
	v_cvt_f32_i32_e32 v50, v30
	v_cvt_f32_i32_e32 v51, v31
	v_cvt_f32_i32_e32 v44, v20
	v_cvt_f32_i32_e32 v45, v21
	v_cvt_f32_i32_e32 v48, v22
	v_cvt_f32_i32_e32 v49, v23
	v_cvt_f32_i32_e32 v38, v40
	v_cvt_f32_i32_e32 v39, v41
	v_cvt_f32_i32_e32 v42, v42
	v_cvt_f32_i32_e32 v43, v43
	v_cvt_f32_i32_e32 v36, v32
	v_cvt_f32_i32_e32 v37, v33
	v_cvt_f32_i32_e32 v40, v34
	v_cvt_f32_i32_e32 v41, v35
	v_cvt_f32_i32_e32 v30, v12
	v_cvt_f32_i32_e32 v31, v13
	v_cvt_f32_i32_e32 v34, v14
	v_cvt_f32_i32_e32 v35, v15
	v_cvt_f32_i32_e32 v28, v8
	v_cvt_f32_i32_e32 v29, v9
	v_cvt_f32_i32_e32 v32, v10
	v_cvt_f32_i32_e32 v33, v11
	v_cvt_f32_i32_e32 v22, v24
	v_cvt_f32_i32_e32 v23, v25
	v_cvt_f32_i32_e32 v26, v26
	v_cvt_f32_i32_e32 v27, v27
	v_cvt_f32_i32_e32 v20, v16
	v_cvt_f32_i32_e32 v21, v17
	v_cvt_f32_i32_e32 v24, v18
	v_cvt_f32_i32_e32 v25, v19
	v_cvt_f32_i32_e32 v14, v4
	v_cvt_f32_i32_e32 v15, v5
	v_cvt_f32_i32_e32 v18, v6
	v_cvt_f32_i32_e32 v19, v7
	v_cvt_f32_i32_e32 v12, v0
	v_cvt_f32_i32_e32 v13, v1
	v_cvt_f32_i32_e32 v16, v2
	v_cvt_f32_i32_e32 v17, v3
	s_and_b64 vcc, exec, s[20:21]
	s_cbranch_vccz .LBB0_1477
